# GEMM K-loops: the two MFMAs of each accumulator (k=0..31, k=32..63) issued back-to-back instead of 8 apart
# speedup vs baseline: 1.0139x; 1.0139x over previous
.LBB0_383:
	s_ashr_i32 s67, s66, 31
	s_lshl_b64 s[26:27], s[66:67], 19
	s_add_u32 s26, s40, s26
	s_addc_u32 s27, s41, s27
	s_and_b64 s[34:35], s[8:9], exec
	s_cselect_b32 s34, s27, s5
	s_cselect_b32 s35, s26, s4
	s_ashr_i32 s29, s28, 31
	s_lshl_b64 s[38:39], s[28:29], 19
	s_add_u32 s62, s10, s38
	s_addc_u32 s63, s11, s39
	s_and_b64 s[38:39], s[8:9], exec
	s_cselect_b32 s29, s63, s83
	s_cselect_b32 s38, s62, s82
	s_add_u32 s39, s82, 0x100
	s_addc_u32 s67, s83, 0
	s_mov_b32 s94, -2
	s_mov_b64 vcc, 0
	v_lshl_add_u64 v[132:133], s[4:5], 0, v[168:169]
	ds_read_b128 v[134:137], v199
	ds_read_b128 v[138:141], v200
	ds_read_b128 v[142:145], v201
	ds_read_b128 v[146:149], v202
	ds_read_b128 v[150:153], v203
	ds_read_b128 v[174:177], v204
	ds_read_b128 v[178:181], v205
	ds_read_b128 v[182:185], v206
	s_add_u32 s24, s4, vcc_lo
	s_addc_u32 s25, s5, vcc_hi
	s_add_u32 s24, s24, 0x100
	s_addc_u32 s25, s25, 0
	s_add_u32 s82, s39, vcc_lo
	s_addc_u32 s83, s67, vcc_hi
	s_cmpk_eq_i32 vcc_lo, 0x700
	s_cselect_b32 s87, s29, s83
	s_cselect_b32 s86, s38, s82
	s_cselect_b32 s83, s34, s25
	s_cselect_b32 s82, s35, s24
	v_lshl_add_u64 v[154:155], v[132:133], 0, vcc
	v_lshl_add_u64 v[250:251], v[154:155], 0, s[48:49]
	s_add_i32 m0, s79, 0x8000
	s_mov_b64 s[24:25], 0x20080
	ds_read_b128 v[218:221], v207
	ds_read_b128 v[222:225], v207 offset:2048
	ds_read_b128 v[226:229], v208
	ds_read_b128 v[230:233], v208 offset:2048
	ds_read_b128 v[234:237], v207 offset:4096
	ds_read_b128 v[238:241], v207 offset:6144
	ds_read_b128 v[242:245], v208 offset:4096
	ds_read_b128 v[246:249], v208 offset:6144
	global_load_lds_dwordx4 v[250:251], off
	v_lshl_add_u64 v[250:251], v[154:155], 0, s[24:25]
	s_add_i32 m0, s79, 0xa000
	s_mov_b64 s[24:25], 0x60080
	global_load_lds_dwordx4 v[250:251], off
	v_lshl_add_u64 v[250:251], v[154:155], 0, s[50:51]
	s_add_i32 m0, s79, 0xc000
	v_lshl_add_u64 v[154:155], v[154:155], 0, s[24:25]
	global_load_lds_dwordx4 v[250:251], off
	s_add_i32 m0, s79, 0xe000
	s_nop 0
	global_load_lds_dwordx4 v[154:155], off
	s_waitcnt lgkmcnt(0)
	s_barrier
	v_mfma_f32_16x16x32_bf16 v[128:131], v[134:137], v[218:221], 0
	v_mfma_f32_16x16x32_bf16 v[128:131], v[138:141], v[226:229], v[128:131]
	v_mfma_f32_16x16x32_bf16 v[124:127], v[142:145], v[218:221], 0
	v_mfma_f32_16x16x32_bf16 v[124:127], v[146:149], v[226:229], v[124:127]
	v_mfma_f32_16x16x32_bf16 v[112:115], v[134:137], v[222:225], 0
	v_mfma_f32_16x16x32_bf16 v[112:115], v[138:141], v[230:233], v[112:115]
	v_mfma_f32_16x16x32_bf16 v[108:111], v[142:145], v[222:225], 0
	v_mfma_f32_16x16x32_bf16 v[108:111], v[146:149], v[230:233], v[108:111]
	v_mfma_f32_16x16x32_bf16 v[96:99], v[134:137], v[234:237], 0
	v_mfma_f32_16x16x32_bf16 v[96:99], v[138:141], v[242:245], v[96:99]
	v_mfma_f32_16x16x32_bf16 v[92:95], v[142:145], v[234:237], 0
	v_mfma_f32_16x16x32_bf16 v[92:95], v[146:149], v[242:245], v[92:95]
	v_mfma_f32_16x16x32_bf16 v[80:83], v[134:137], v[238:241], 0
	v_mfma_f32_16x16x32_bf16 v[80:83], v[138:141], v[246:249], v[80:83]
	v_mfma_f32_16x16x32_bf16 v[76:79], v[142:145], v[238:241], 0
	v_mfma_f32_16x16x32_bf16 v[76:79], v[146:149], v[246:249], v[76:79]
	v_mfma_f32_16x16x32_bf16 v[120:123], v[150:153], v[218:221], 0
	v_mfma_f32_16x16x32_bf16 v[120:123], v[174:177], v[226:229], v[120:123]
	v_mfma_f32_16x16x32_bf16 v[116:119], v[178:181], v[218:221], 0
	v_mfma_f32_16x16x32_bf16 v[116:119], v[182:185], v[226:229], v[116:119]
	v_mfma_f32_16x16x32_bf16 v[104:107], v[150:153], v[222:225], 0
	v_mfma_f32_16x16x32_bf16 v[104:107], v[174:177], v[230:233], v[104:107]
	v_mfma_f32_16x16x32_bf16 v[100:103], v[178:181], v[222:225], 0
	v_mfma_f32_16x16x32_bf16 v[100:103], v[182:185], v[230:233], v[100:103]
	v_mfma_f32_16x16x32_bf16 v[88:91], v[150:153], v[234:237], 0
	v_mfma_f32_16x16x32_bf16 v[88:91], v[174:177], v[242:245], v[88:91]
	v_mfma_f32_16x16x32_bf16 v[84:87], v[178:181], v[234:237], 0
	v_mfma_f32_16x16x32_bf16 v[84:87], v[182:185], v[242:245], v[84:87]
	v_mfma_f32_16x16x32_bf16 v[72:75], v[150:153], v[238:241], 0
	v_mfma_f32_16x16x32_bf16 v[72:75], v[174:177], v[246:249], v[72:75]
	v_mfma_f32_16x16x32_bf16 v[68:71], v[178:181], v[238:241], 0
	v_mfma_f32_16x16x32_bf16 v[68:71], v[182:185], v[246:249], v[68:71]
	s_barrier
	s_add_i32 s24, s1, s77
	v_lshl_add_u64 v[154:155], s[86:87], 0, v[158:159]
	s_mov_b32 m0, s24
	ds_read_b128 v[218:221], v207 offset:16384
	ds_read_b128 v[222:225], v207 offset:18432
	ds_read_b128 v[226:229], v208 offset:16384
	ds_read_b128 v[230:233], v208 offset:18432
	ds_read_b128 v[234:237], v207 offset:20480
	ds_read_b128 v[238:241], v207 offset:22528
	ds_read_b128 v[242:245], v208 offset:20480
	ds_read_b128 v[246:249], v208 offset:22528
	global_load_lds_dwordx4 v[154:155], off
	v_lshl_add_u64 v[250:251], v[154:155], 0, s[14:15]
	s_add_i32 m0, s24, 0x2000
	s_add_i32 s24, s12, s77
	global_load_lds_dwordx4 v[250:251], off
	v_lshl_add_u64 v[250:251], v[154:155], 0, s[16:17]
	s_mov_b32 m0, s24
	s_nop 0
	global_load_lds_dwordx4 v[250:251], off
	v_lshl_add_u64 v[250:251], v[154:155], 0, s[18:19]
	s_add_i32 m0, s24, 0x2000
	s_nop 0
	global_load_lds_dwordx4 v[250:251], off
	s_waitcnt vmcnt(4)
	s_waitcnt lgkmcnt(0)
	s_barrier
	v_mfma_f32_16x16x32_bf16 v[64:67], v[134:137], v[218:221], 0
	v_mfma_f32_16x16x32_bf16 v[64:67], v[138:141], v[226:229], v[64:67]
	v_mfma_f32_16x16x32_bf16 v[60:63], v[142:145], v[218:221], 0
	v_mfma_f32_16x16x32_bf16 v[60:63], v[146:149], v[226:229], v[60:63]
	v_mfma_f32_16x16x32_bf16 v[48:51], v[134:137], v[222:225], 0
	v_mfma_f32_16x16x32_bf16 v[48:51], v[138:141], v[230:233], v[48:51]
	v_mfma_f32_16x16x32_bf16 v[44:47], v[142:145], v[222:225], 0
	v_mfma_f32_16x16x32_bf16 v[44:47], v[146:149], v[230:233], v[44:47]
	v_mfma_f32_16x16x32_bf16 v[32:35], v[134:137], v[234:237], 0
	v_mfma_f32_16x16x32_bf16 v[32:35], v[138:141], v[242:245], v[32:35]
	v_mfma_f32_16x16x32_bf16 v[28:31], v[142:145], v[234:237], 0
	v_mfma_f32_16x16x32_bf16 v[28:31], v[146:149], v[242:245], v[28:31]
	v_mfma_f32_16x16x32_bf16 v[16:19], v[134:137], v[238:241], 0
	v_mfma_f32_16x16x32_bf16 v[16:19], v[138:141], v[246:249], v[16:19]
	v_mfma_f32_16x16x32_bf16 v[12:15], v[142:145], v[238:241], 0
	v_mfma_f32_16x16x32_bf16 v[12:15], v[146:149], v[246:249], v[12:15]
	v_mfma_f32_16x16x32_bf16 v[56:59], v[150:153], v[218:221], 0
	v_mfma_f32_16x16x32_bf16 v[56:59], v[174:177], v[226:229], v[56:59]
	v_mfma_f32_16x16x32_bf16 v[52:55], v[178:181], v[218:221], 0
	v_mfma_f32_16x16x32_bf16 v[52:55], v[182:185], v[226:229], v[52:55]
	v_mfma_f32_16x16x32_bf16 v[40:43], v[150:153], v[222:225], 0
	v_mfma_f32_16x16x32_bf16 v[40:43], v[174:177], v[230:233], v[40:43]
	v_mfma_f32_16x16x32_bf16 v[36:39], v[178:181], v[222:225], 0
	v_mfma_f32_16x16x32_bf16 v[36:39], v[182:185], v[230:233], v[36:39]
	v_mfma_f32_16x16x32_bf16 v[24:27], v[150:153], v[234:237], 0
	v_mfma_f32_16x16x32_bf16 v[24:27], v[174:177], v[242:245], v[24:27]
	v_mfma_f32_16x16x32_bf16 v[20:23], v[178:181], v[234:237], 0
	v_mfma_f32_16x16x32_bf16 v[20:23], v[182:185], v[242:245], v[20:23]
	v_mfma_f32_16x16x32_bf16 v[8:11], v[150:153], v[238:241], 0
	v_mfma_f32_16x16x32_bf16 v[8:11], v[174:177], v[246:249], v[8:11]
	v_mfma_f32_16x16x32_bf16 v[4:7], v[178:181], v[238:241], 0
	v_mfma_f32_16x16x32_bf16 v[4:7], v[182:185], v[246:249], v[4:7]
	s_barrier
	ds_read_b128 v[134:137], v213
	ds_read_b128 v[138:141], v214
	ds_read_b128 v[142:145], v209
	ds_read_b128 v[146:149], v210
	ds_read_b128 v[150:153], v215
	ds_read_b128 v[174:177], v216
	ds_read_b128 v[178:181], v211
	ds_read_b128 v[182:185], v212
	s_mov_b32 m0, s79
	v_lshl_add_u64 v[250:251], s[82:83], 0, v[0:1]
	ds_read_b128 v[218:221], v207 offset:32768
	ds_read_b128 v[222:225], v207 offset:34816
	ds_read_b128 v[226:229], v208 offset:32768
	ds_read_b128 v[230:233], v208 offset:34816
	ds_read_b128 v[234:237], v207 offset:36864
	ds_read_b128 v[238:241], v207 offset:38912
	ds_read_b128 v[242:245], v208 offset:36864
	ds_read_b128 v[246:249], v208 offset:38912
	global_load_lds_dwordx4 v[250:251], off
	v_lshl_add_u64 v[252:253], v[250:251], 0, s[20:21]
	s_mov_b32 m0, s81
	s_nop 0
	global_load_lds_dwordx4 v[252:253], off
	v_lshl_add_u64 v[252:253], v[250:251], 0, s[14:15]
	s_mov_b32 m0, s97
	v_lshl_add_u64 v[250:251], v[250:251], 0, s[22:23]
	global_load_lds_dwordx4 v[252:253], off
	s_mov_b32 m0, s64
	s_nop 0
	global_load_lds_dwordx4 v[250:251], off
	s_waitcnt vmcnt(8)
	s_waitcnt lgkmcnt(0)
	s_barrier
	v_mfma_f32_16x16x32_bf16 v[128:131], v[134:137], v[218:221], v[128:131]
	v_mfma_f32_16x16x32_bf16 v[128:131], v[138:141], v[226:229], v[128:131]
	v_mfma_f32_16x16x32_bf16 v[124:127], v[142:145], v[218:221], v[124:127]
	v_mfma_f32_16x16x32_bf16 v[124:127], v[146:149], v[226:229], v[124:127]
	v_mfma_f32_16x16x32_bf16 v[112:115], v[134:137], v[222:225], v[112:115]
	v_mfma_f32_16x16x32_bf16 v[112:115], v[138:141], v[230:233], v[112:115]
	v_mfma_f32_16x16x32_bf16 v[108:111], v[142:145], v[222:225], v[108:111]
	v_mfma_f32_16x16x32_bf16 v[108:111], v[146:149], v[230:233], v[108:111]
	v_mfma_f32_16x16x32_bf16 v[96:99], v[134:137], v[234:237], v[96:99]
	v_mfma_f32_16x16x32_bf16 v[96:99], v[138:141], v[242:245], v[96:99]
	v_mfma_f32_16x16x32_bf16 v[92:95], v[142:145], v[234:237], v[92:95]
	v_mfma_f32_16x16x32_bf16 v[92:95], v[146:149], v[242:245], v[92:95]
	v_mfma_f32_16x16x32_bf16 v[80:83], v[134:137], v[238:241], v[80:83]
	v_mfma_f32_16x16x32_bf16 v[80:83], v[138:141], v[246:249], v[80:83]
	v_mfma_f32_16x16x32_bf16 v[76:79], v[142:145], v[238:241], v[76:79]
	v_mfma_f32_16x16x32_bf16 v[76:79], v[146:149], v[246:249], v[76:79]
	v_mfma_f32_16x16x32_bf16 v[120:123], v[150:153], v[218:221], v[120:123]
	v_mfma_f32_16x16x32_bf16 v[120:123], v[174:177], v[226:229], v[120:123]
	v_mfma_f32_16x16x32_bf16 v[116:119], v[178:181], v[218:221], v[116:119]
	v_mfma_f32_16x16x32_bf16 v[116:119], v[182:185], v[226:229], v[116:119]
	v_mfma_f32_16x16x32_bf16 v[104:107], v[150:153], v[222:225], v[104:107]
	v_mfma_f32_16x16x32_bf16 v[104:107], v[174:177], v[230:233], v[104:107]
	v_mfma_f32_16x16x32_bf16 v[100:103], v[178:181], v[222:225], v[100:103]
	v_mfma_f32_16x16x32_bf16 v[100:103], v[182:185], v[230:233], v[100:103]
	v_mfma_f32_16x16x32_bf16 v[88:91], v[150:153], v[234:237], v[88:91]
	v_mfma_f32_16x16x32_bf16 v[88:91], v[174:177], v[242:245], v[88:91]
	v_mfma_f32_16x16x32_bf16 v[84:87], v[178:181], v[234:237], v[84:87]
	v_mfma_f32_16x16x32_bf16 v[84:87], v[182:185], v[242:245], v[84:87]
	v_mfma_f32_16x16x32_bf16 v[72:75], v[150:153], v[238:241], v[72:75]
	v_mfma_f32_16x16x32_bf16 v[72:75], v[174:177], v[246:249], v[72:75]
	v_mfma_f32_16x16x32_bf16 v[68:71], v[178:181], v[238:241], v[68:71]
	v_mfma_f32_16x16x32_bf16 v[68:71], v[182:185], v[246:249], v[68:71]
	s_barrier
	s_add_i32 s24, s70, s77
	v_lshl_add_u64 v[250:251], v[154:155], 0, s[48:49]
	s_mov_b32 m0, s24
	ds_read_b128 v[218:221], v207 offset:49152
	ds_read_b128 v[222:225], v207 offset:51200
	ds_read_b128 v[226:229], v208 offset:49152
	ds_read_b128 v[230:233], v208 offset:51200
	ds_read_b128 v[234:237], v207 offset:53248
	ds_read_b128 v[238:241], v207 offset:55296
	ds_read_b128 v[242:245], v208 offset:53248
	ds_read_b128 v[246:249], v208 offset:55296
	global_load_lds_dwordx4 v[250:251], off
	v_lshl_add_u64 v[250:251], v[154:155], 0, s[50:51]
	s_add_i32 m0, s24, 0x2000
	s_add_i32 s24, s71, s77
	global_load_lds_dwordx4 v[250:251], off
	v_lshl_add_u64 v[250:251], v[154:155], 0, s[52:53]
	s_mov_b32 m0, s24
	v_lshl_add_u64 v[154:155], v[154:155], 0, s[54:55]
	global_load_lds_dwordx4 v[250:251], off
	s_add_i32 m0, s24, 0x2000
	s_nop 0
	global_load_lds_dwordx4 v[154:155], off
	s_waitcnt vmcnt(4)
	s_waitcnt lgkmcnt(0)
	s_barrier
	v_mfma_f32_16x16x32_bf16 v[64:67], v[134:137], v[218:221], v[64:67]
	v_mfma_f32_16x16x32_bf16 v[64:67], v[138:141], v[226:229], v[64:67]
	v_mfma_f32_16x16x32_bf16 v[60:63], v[142:145], v[218:221], v[60:63]
	v_mfma_f32_16x16x32_bf16 v[60:63], v[146:149], v[226:229], v[60:63]
	v_mfma_f32_16x16x32_bf16 v[48:51], v[134:137], v[222:225], v[48:51]
	v_mfma_f32_16x16x32_bf16 v[48:51], v[138:141], v[230:233], v[48:51]
	v_mfma_f32_16x16x32_bf16 v[44:47], v[142:145], v[222:225], v[44:47]
	v_mfma_f32_16x16x32_bf16 v[44:47], v[146:149], v[230:233], v[44:47]
	v_mfma_f32_16x16x32_bf16 v[32:35], v[134:137], v[234:237], v[32:35]
	v_mfma_f32_16x16x32_bf16 v[32:35], v[138:141], v[242:245], v[32:35]
	v_mfma_f32_16x16x32_bf16 v[28:31], v[142:145], v[234:237], v[28:31]
	v_mfma_f32_16x16x32_bf16 v[28:31], v[146:149], v[242:245], v[28:31]
	v_mfma_f32_16x16x32_bf16 v[16:19], v[134:137], v[238:241], v[16:19]
	v_mfma_f32_16x16x32_bf16 v[16:19], v[138:141], v[246:249], v[16:19]
	v_mfma_f32_16x16x32_bf16 v[12:15], v[142:145], v[238:241], v[12:15]
	v_mfma_f32_16x16x32_bf16 v[12:15], v[146:149], v[246:249], v[12:15]
	v_mfma_f32_16x16x32_bf16 v[56:59], v[150:153], v[218:221], v[56:59]
	v_mfma_f32_16x16x32_bf16 v[56:59], v[174:177], v[226:229], v[56:59]
	v_mfma_f32_16x16x32_bf16 v[52:55], v[178:181], v[218:221], v[52:55]
	v_mfma_f32_16x16x32_bf16 v[52:55], v[182:185], v[226:229], v[52:55]
	v_mfma_f32_16x16x32_bf16 v[40:43], v[150:153], v[222:225], v[40:43]
	v_mfma_f32_16x16x32_bf16 v[40:43], v[174:177], v[230:233], v[40:43]
	v_mfma_f32_16x16x32_bf16 v[36:39], v[178:181], v[222:225], v[36:39]
	v_mfma_f32_16x16x32_bf16 v[36:39], v[182:185], v[230:233], v[36:39]
	v_mfma_f32_16x16x32_bf16 v[24:27], v[150:153], v[234:237], v[24:27]
	v_mfma_f32_16x16x32_bf16 v[24:27], v[174:177], v[242:245], v[24:27]
	v_mfma_f32_16x16x32_bf16 v[20:23], v[178:181], v[234:237], v[20:23]
	v_mfma_f32_16x16x32_bf16 v[20:23], v[182:185], v[242:245], v[20:23]
	v_mfma_f32_16x16x32_bf16 v[8:11], v[150:153], v[238:241], v[8:11]
	v_mfma_f32_16x16x32_bf16 v[8:11], v[174:177], v[246:249], v[8:11]
	v_mfma_f32_16x16x32_bf16 v[4:7], v[178:181], v[238:241], v[4:7]
	v_mfma_f32_16x16x32_bf16 v[4:7], v[182:185], v[246:249], v[4:7]
	s_barrier
	s_add_i32 s94, s94, 2
	s_add_u32 vcc_lo, vcc_lo, 0x100
	s_addc_u32 vcc_hi, vcc_hi, 0
	s_cmp_gt_u32 s94, 13
.LBB0_384:
	ds_read_b128 v[134:137], v199
	ds_read_b128 v[138:141], v200
	ds_read_b128 v[142:145], v201
	ds_read_b128 v[146:149], v202
	ds_read_b128 v[150:153], v203
	ds_read_b128 v[174:177], v204
	ds_read_b128 v[178:181], v205
	ds_read_b128 v[182:185], v206
	s_add_u32 s24, s4, vcc_lo
	s_addc_u32 s25, s5, vcc_hi
	s_add_u32 s24, s24, 0x100
	s_addc_u32 s25, s25, 0
	s_add_u32 s82, s39, vcc_lo
	s_addc_u32 s83, s67, vcc_hi
	s_cmpk_eq_i32 vcc_lo, 0x700
	s_cselect_b32 s87, s29, s83
	s_cselect_b32 s86, s38, s82
	s_cselect_b32 s83, s34, s25
	s_cselect_b32 s82, s35, s24
	v_lshl_add_u64 v[154:155], v[132:133], 0, vcc
	v_lshl_add_u64 v[250:251], v[154:155], 0, s[48:49]
	s_add_i32 m0, s79, 0x8000
	s_mov_b64 s[24:25], 0x20080
	ds_read_b128 v[218:221], v207
	ds_read_b128 v[222:225], v207 offset:2048
	ds_read_b128 v[226:229], v208
	ds_read_b128 v[230:233], v208 offset:2048
	ds_read_b128 v[234:237], v207 offset:4096
	ds_read_b128 v[238:241], v207 offset:6144
	ds_read_b128 v[242:245], v208 offset:4096
	ds_read_b128 v[246:249], v208 offset:6144
	global_load_lds_dwordx4 v[250:251], off
	v_lshl_add_u64 v[250:251], v[154:155], 0, s[24:25]
	s_add_i32 m0, s79, 0xa000
	s_mov_b64 s[24:25], 0x60080
	global_load_lds_dwordx4 v[250:251], off
	v_lshl_add_u64 v[250:251], v[154:155], 0, s[50:51]
	s_add_i32 m0, s79, 0xc000
	v_lshl_add_u64 v[154:155], v[154:155], 0, s[24:25]
	global_load_lds_dwordx4 v[250:251], off
	s_add_i32 m0, s79, 0xe000
	s_nop 0
	global_load_lds_dwordx4 v[154:155], off
	s_waitcnt vmcnt(8)
	s_waitcnt lgkmcnt(0)
	s_barrier
	v_mfma_f32_16x16x32_bf16 v[128:131], v[134:137], v[218:221], v[128:131]
	v_mfma_f32_16x16x32_bf16 v[128:131], v[138:141], v[226:229], v[128:131]
	v_mfma_f32_16x16x32_bf16 v[124:127], v[142:145], v[218:221], v[124:127]
	v_mfma_f32_16x16x32_bf16 v[124:127], v[146:149], v[226:229], v[124:127]
	v_mfma_f32_16x16x32_bf16 v[112:115], v[134:137], v[222:225], v[112:115]
	v_mfma_f32_16x16x32_bf16 v[112:115], v[138:141], v[230:233], v[112:115]
	v_mfma_f32_16x16x32_bf16 v[108:111], v[142:145], v[222:225], v[108:111]
	v_mfma_f32_16x16x32_bf16 v[108:111], v[146:149], v[230:233], v[108:111]
	v_mfma_f32_16x16x32_bf16 v[96:99], v[134:137], v[234:237], v[96:99]
	v_mfma_f32_16x16x32_bf16 v[96:99], v[138:141], v[242:245], v[96:99]
	v_mfma_f32_16x16x32_bf16 v[92:95], v[142:145], v[234:237], v[92:95]
	v_mfma_f32_16x16x32_bf16 v[92:95], v[146:149], v[242:245], v[92:95]
	v_mfma_f32_16x16x32_bf16 v[80:83], v[134:137], v[238:241], v[80:83]
	v_mfma_f32_16x16x32_bf16 v[80:83], v[138:141], v[246:249], v[80:83]
	v_mfma_f32_16x16x32_bf16 v[76:79], v[142:145], v[238:241], v[76:79]
	v_mfma_f32_16x16x32_bf16 v[76:79], v[146:149], v[246:249], v[76:79]
	v_mfma_f32_16x16x32_bf16 v[120:123], v[150:153], v[218:221], v[120:123]
	v_mfma_f32_16x16x32_bf16 v[120:123], v[174:177], v[226:229], v[120:123]
	v_mfma_f32_16x16x32_bf16 v[116:119], v[178:181], v[218:221], v[116:119]
	v_mfma_f32_16x16x32_bf16 v[116:119], v[182:185], v[226:229], v[116:119]
	v_mfma_f32_16x16x32_bf16 v[104:107], v[150:153], v[222:225], v[104:107]
	v_mfma_f32_16x16x32_bf16 v[104:107], v[174:177], v[230:233], v[104:107]
	v_mfma_f32_16x16x32_bf16 v[100:103], v[178:181], v[222:225], v[100:103]
	v_mfma_f32_16x16x32_bf16 v[100:103], v[182:185], v[230:233], v[100:103]
	v_mfma_f32_16x16x32_bf16 v[88:91], v[150:153], v[234:237], v[88:91]
	v_mfma_f32_16x16x32_bf16 v[88:91], v[174:177], v[242:245], v[88:91]
	v_mfma_f32_16x16x32_bf16 v[84:87], v[178:181], v[234:237], v[84:87]
	v_mfma_f32_16x16x32_bf16 v[84:87], v[182:185], v[242:245], v[84:87]
	v_mfma_f32_16x16x32_bf16 v[72:75], v[150:153], v[238:241], v[72:75]
	v_mfma_f32_16x16x32_bf16 v[72:75], v[174:177], v[246:249], v[72:75]
	v_mfma_f32_16x16x32_bf16 v[68:71], v[178:181], v[238:241], v[68:71]
	v_mfma_f32_16x16x32_bf16 v[68:71], v[182:185], v[246:249], v[68:71]
	s_barrier
	s_add_i32 s24, s1, s77
	v_lshl_add_u64 v[154:155], s[86:87], 0, v[158:159]
	s_mov_b32 m0, s24
	ds_read_b128 v[218:221], v207 offset:16384
	ds_read_b128 v[222:225], v207 offset:18432
	ds_read_b128 v[226:229], v208 offset:16384
	ds_read_b128 v[230:233], v208 offset:18432
	ds_read_b128 v[234:237], v207 offset:20480
	ds_read_b128 v[238:241], v207 offset:22528
	ds_read_b128 v[242:245], v208 offset:20480
	ds_read_b128 v[246:249], v208 offset:22528
	global_load_lds_dwordx4 v[154:155], off
	v_lshl_add_u64 v[250:251], v[154:155], 0, s[14:15]
	s_add_i32 m0, s24, 0x2000
	s_add_i32 s24, s12, s77
	global_load_lds_dwordx4 v[250:251], off
	v_lshl_add_u64 v[250:251], v[154:155], 0, s[16:17]
	s_mov_b32 m0, s24
	s_nop 0
	global_load_lds_dwordx4 v[250:251], off
	v_lshl_add_u64 v[250:251], v[154:155], 0, s[18:19]
	s_add_i32 m0, s24, 0x2000
	s_nop 0
	global_load_lds_dwordx4 v[250:251], off
	s_waitcnt vmcnt(4)
	s_waitcnt lgkmcnt(0)
	s_barrier
	v_mfma_f32_16x16x32_bf16 v[64:67], v[134:137], v[218:221], v[64:67]
	v_mfma_f32_16x16x32_bf16 v[64:67], v[138:141], v[226:229], v[64:67]
	v_mfma_f32_16x16x32_bf16 v[60:63], v[142:145], v[218:221], v[60:63]
	v_mfma_f32_16x16x32_bf16 v[60:63], v[146:149], v[226:229], v[60:63]
	v_mfma_f32_16x16x32_bf16 v[48:51], v[134:137], v[222:225], v[48:51]
	v_mfma_f32_16x16x32_bf16 v[48:51], v[138:141], v[230:233], v[48:51]
	v_mfma_f32_16x16x32_bf16 v[44:47], v[142:145], v[222:225], v[44:47]
	v_mfma_f32_16x16x32_bf16 v[44:47], v[146:149], v[230:233], v[44:47]
	v_mfma_f32_16x16x32_bf16 v[32:35], v[134:137], v[234:237], v[32:35]
	v_mfma_f32_16x16x32_bf16 v[32:35], v[138:141], v[242:245], v[32:35]
	v_mfma_f32_16x16x32_bf16 v[28:31], v[142:145], v[234:237], v[28:31]
	v_mfma_f32_16x16x32_bf16 v[28:31], v[146:149], v[242:245], v[28:31]
	v_mfma_f32_16x16x32_bf16 v[16:19], v[134:137], v[238:241], v[16:19]
	v_mfma_f32_16x16x32_bf16 v[16:19], v[138:141], v[246:249], v[16:19]
	v_mfma_f32_16x16x32_bf16 v[12:15], v[142:145], v[238:241], v[12:15]
	v_mfma_f32_16x16x32_bf16 v[12:15], v[146:149], v[246:249], v[12:15]
	v_mfma_f32_16x16x32_bf16 v[56:59], v[150:153], v[218:221], v[56:59]
	v_mfma_f32_16x16x32_bf16 v[56:59], v[174:177], v[226:229], v[56:59]
	v_mfma_f32_16x16x32_bf16 v[52:55], v[178:181], v[218:221], v[52:55]
	v_mfma_f32_16x16x32_bf16 v[52:55], v[182:185], v[226:229], v[52:55]
	v_mfma_f32_16x16x32_bf16 v[40:43], v[150:153], v[222:225], v[40:43]
	v_mfma_f32_16x16x32_bf16 v[40:43], v[174:177], v[230:233], v[40:43]
	v_mfma_f32_16x16x32_bf16 v[36:39], v[178:181], v[222:225], v[36:39]
	v_mfma_f32_16x16x32_bf16 v[36:39], v[182:185], v[230:233], v[36:39]
	v_mfma_f32_16x16x32_bf16 v[24:27], v[150:153], v[234:237], v[24:27]
	v_mfma_f32_16x16x32_bf16 v[24:27], v[174:177], v[242:245], v[24:27]
	v_mfma_f32_16x16x32_bf16 v[20:23], v[178:181], v[234:237], v[20:23]
	v_mfma_f32_16x16x32_bf16 v[20:23], v[182:185], v[242:245], v[20:23]
	v_mfma_f32_16x16x32_bf16 v[8:11], v[150:153], v[238:241], v[8:11]
	v_mfma_f32_16x16x32_bf16 v[8:11], v[174:177], v[246:249], v[8:11]
	v_mfma_f32_16x16x32_bf16 v[4:7], v[178:181], v[238:241], v[4:7]
	v_mfma_f32_16x16x32_bf16 v[4:7], v[182:185], v[246:249], v[4:7]
	s_barrier
	ds_read_b128 v[134:137], v213
	ds_read_b128 v[138:141], v214
	ds_read_b128 v[142:145], v209
	ds_read_b128 v[146:149], v210
	ds_read_b128 v[150:153], v215
	ds_read_b128 v[174:177], v216
	ds_read_b128 v[178:181], v211
	ds_read_b128 v[182:185], v212
	s_mov_b32 m0, s79
	v_lshl_add_u64 v[250:251], s[82:83], 0, v[0:1]
	ds_read_b128 v[218:221], v207 offset:32768
	ds_read_b128 v[222:225], v207 offset:34816
	ds_read_b128 v[226:229], v208 offset:32768
	ds_read_b128 v[230:233], v208 offset:34816
	ds_read_b128 v[234:237], v207 offset:36864
	ds_read_b128 v[238:241], v207 offset:38912
	ds_read_b128 v[242:245], v208 offset:36864
	ds_read_b128 v[246:249], v208 offset:38912
	global_load_lds_dwordx4 v[250:251], off
	v_lshl_add_u64 v[252:253], v[250:251], 0, s[20:21]
	s_mov_b32 m0, s81
	s_nop 0
	global_load_lds_dwordx4 v[252:253], off
	v_lshl_add_u64 v[252:253], v[250:251], 0, s[14:15]
	s_mov_b32 m0, s97
	v_lshl_add_u64 v[250:251], v[250:251], 0, s[22:23]
	global_load_lds_dwordx4 v[252:253], off
	s_mov_b32 m0, s64
	s_nop 0
	global_load_lds_dwordx4 v[250:251], off
	s_waitcnt vmcnt(8)
	s_waitcnt lgkmcnt(0)
	s_barrier
	v_mfma_f32_16x16x32_bf16 v[128:131], v[134:137], v[218:221], v[128:131]
	v_mfma_f32_16x16x32_bf16 v[128:131], v[138:141], v[226:229], v[128:131]
	v_mfma_f32_16x16x32_bf16 v[124:127], v[142:145], v[218:221], v[124:127]
	v_mfma_f32_16x16x32_bf16 v[124:127], v[146:149], v[226:229], v[124:127]
	v_mfma_f32_16x16x32_bf16 v[112:115], v[134:137], v[222:225], v[112:115]
	v_mfma_f32_16x16x32_bf16 v[112:115], v[138:141], v[230:233], v[112:115]
	v_mfma_f32_16x16x32_bf16 v[108:111], v[142:145], v[222:225], v[108:111]
	v_mfma_f32_16x16x32_bf16 v[108:111], v[146:149], v[230:233], v[108:111]
	v_mfma_f32_16x16x32_bf16 v[96:99], v[134:137], v[234:237], v[96:99]
	v_mfma_f32_16x16x32_bf16 v[96:99], v[138:141], v[242:245], v[96:99]
	v_mfma_f32_16x16x32_bf16 v[92:95], v[142:145], v[234:237], v[92:95]
	v_mfma_f32_16x16x32_bf16 v[92:95], v[146:149], v[242:245], v[92:95]
	v_mfma_f32_16x16x32_bf16 v[80:83], v[134:137], v[238:241], v[80:83]
	v_mfma_f32_16x16x32_bf16 v[80:83], v[138:141], v[246:249], v[80:83]
	v_mfma_f32_16x16x32_bf16 v[76:79], v[142:145], v[238:241], v[76:79]
	v_mfma_f32_16x16x32_bf16 v[76:79], v[146:149], v[246:249], v[76:79]
	v_mfma_f32_16x16x32_bf16 v[120:123], v[150:153], v[218:221], v[120:123]
	v_mfma_f32_16x16x32_bf16 v[120:123], v[174:177], v[226:229], v[120:123]
	v_mfma_f32_16x16x32_bf16 v[116:119], v[178:181], v[218:221], v[116:119]
	v_mfma_f32_16x16x32_bf16 v[116:119], v[182:185], v[226:229], v[116:119]
	v_mfma_f32_16x16x32_bf16 v[104:107], v[150:153], v[222:225], v[104:107]
	v_mfma_f32_16x16x32_bf16 v[104:107], v[174:177], v[230:233], v[104:107]
	v_mfma_f32_16x16x32_bf16 v[100:103], v[178:181], v[222:225], v[100:103]
	v_mfma_f32_16x16x32_bf16 v[100:103], v[182:185], v[230:233], v[100:103]
	v_mfma_f32_16x16x32_bf16 v[88:91], v[150:153], v[234:237], v[88:91]
	v_mfma_f32_16x16x32_bf16 v[88:91], v[174:177], v[242:245], v[88:91]
	v_mfma_f32_16x16x32_bf16 v[84:87], v[178:181], v[234:237], v[84:87]
	v_mfma_f32_16x16x32_bf16 v[84:87], v[182:185], v[242:245], v[84:87]
	v_mfma_f32_16x16x32_bf16 v[72:75], v[150:153], v[238:241], v[72:75]
	v_mfma_f32_16x16x32_bf16 v[72:75], v[174:177], v[246:249], v[72:75]
	v_mfma_f32_16x16x32_bf16 v[68:71], v[178:181], v[238:241], v[68:71]
	v_mfma_f32_16x16x32_bf16 v[68:71], v[182:185], v[246:249], v[68:71]
	s_barrier
	s_add_i32 s24, s70, s77
	v_lshl_add_u64 v[250:251], v[154:155], 0, s[48:49]
	s_mov_b32 m0, s24
	ds_read_b128 v[218:221], v207 offset:49152
	ds_read_b128 v[222:225], v207 offset:51200
	ds_read_b128 v[226:229], v208 offset:49152
	ds_read_b128 v[230:233], v208 offset:51200
	ds_read_b128 v[234:237], v207 offset:53248
	ds_read_b128 v[238:241], v207 offset:55296
	ds_read_b128 v[242:245], v208 offset:53248
	ds_read_b128 v[246:249], v208 offset:55296
	global_load_lds_dwordx4 v[250:251], off
	v_lshl_add_u64 v[250:251], v[154:155], 0, s[50:51]
	s_add_i32 m0, s24, 0x2000
	s_add_i32 s24, s71, s77
	global_load_lds_dwordx4 v[250:251], off
	v_lshl_add_u64 v[250:251], v[154:155], 0, s[52:53]
	s_mov_b32 m0, s24
	v_lshl_add_u64 v[154:155], v[154:155], 0, s[54:55]
	global_load_lds_dwordx4 v[250:251], off
	s_add_i32 m0, s24, 0x2000
	s_nop 0
	global_load_lds_dwordx4 v[154:155], off
	s_waitcnt vmcnt(4)
	s_waitcnt lgkmcnt(0)
	s_barrier
	v_mfma_f32_16x16x32_bf16 v[64:67], v[134:137], v[218:221], v[64:67]
	v_mfma_f32_16x16x32_bf16 v[64:67], v[138:141], v[226:229], v[64:67]
	v_mfma_f32_16x16x32_bf16 v[60:63], v[142:145], v[218:221], v[60:63]
	v_mfma_f32_16x16x32_bf16 v[60:63], v[146:149], v[226:229], v[60:63]
	v_mfma_f32_16x16x32_bf16 v[48:51], v[134:137], v[222:225], v[48:51]
	v_mfma_f32_16x16x32_bf16 v[48:51], v[138:141], v[230:233], v[48:51]
	v_mfma_f32_16x16x32_bf16 v[44:47], v[142:145], v[222:225], v[44:47]
	v_mfma_f32_16x16x32_bf16 v[44:47], v[146:149], v[230:233], v[44:47]
	v_mfma_f32_16x16x32_bf16 v[32:35], v[134:137], v[234:237], v[32:35]
	v_mfma_f32_16x16x32_bf16 v[32:35], v[138:141], v[242:245], v[32:35]
	v_mfma_f32_16x16x32_bf16 v[28:31], v[142:145], v[234:237], v[28:31]
	v_mfma_f32_16x16x32_bf16 v[28:31], v[146:149], v[242:245], v[28:31]
	v_mfma_f32_16x16x32_bf16 v[16:19], v[134:137], v[238:241], v[16:19]
	v_mfma_f32_16x16x32_bf16 v[16:19], v[138:141], v[246:249], v[16:19]
	v_mfma_f32_16x16x32_bf16 v[12:15], v[142:145], v[238:241], v[12:15]
	v_mfma_f32_16x16x32_bf16 v[12:15], v[146:149], v[246:249], v[12:15]
	v_mfma_f32_16x16x32_bf16 v[56:59], v[150:153], v[218:221], v[56:59]
	v_mfma_f32_16x16x32_bf16 v[56:59], v[174:177], v[226:229], v[56:59]
	v_mfma_f32_16x16x32_bf16 v[52:55], v[178:181], v[218:221], v[52:55]
	v_mfma_f32_16x16x32_bf16 v[52:55], v[182:185], v[226:229], v[52:55]
	v_mfma_f32_16x16x32_bf16 v[40:43], v[150:153], v[222:225], v[40:43]
	v_mfma_f32_16x16x32_bf16 v[40:43], v[174:177], v[230:233], v[40:43]
	v_mfma_f32_16x16x32_bf16 v[36:39], v[178:181], v[222:225], v[36:39]
	v_mfma_f32_16x16x32_bf16 v[36:39], v[182:185], v[230:233], v[36:39]
	v_mfma_f32_16x16x32_bf16 v[24:27], v[150:153], v[234:237], v[24:27]
	v_mfma_f32_16x16x32_bf16 v[24:27], v[174:177], v[242:245], v[24:27]
	v_mfma_f32_16x16x32_bf16 v[20:23], v[178:181], v[234:237], v[20:23]
	v_mfma_f32_16x16x32_bf16 v[20:23], v[182:185], v[242:245], v[20:23]
	v_mfma_f32_16x16x32_bf16 v[8:11], v[150:153], v[238:241], v[8:11]
	v_mfma_f32_16x16x32_bf16 v[8:11], v[174:177], v[246:249], v[8:11]
	v_mfma_f32_16x16x32_bf16 v[4:7], v[178:181], v[238:241], v[4:7]
	v_mfma_f32_16x16x32_bf16 v[4:7], v[182:185], v[246:249], v[4:7]
	s_barrier
	s_add_i32 s94, s94, 2
	s_add_u32 vcc_lo, vcc_lo, 0x100
	s_addc_u32 vcc_hi, vcc_hi, 0
	s_cmp_gt_u32 s94, 13
	s_cbranch_scc0 .LBB0_384
	s_and_b64 vcc, exec, s[56:57]
	s_cbranch_vccz .LBB0_387
	s_barrier

.LBB0_779:
	v_add_u32_e32 v4, s73, v159
	v_add_u32_e32 v6, s73, v173
	ds_read_b128 v[136:139], v4
	ds_read_b128 v[140:143], v6
	v_add_u32_e32 v4, s77, v159
	s_add_u32 s26, s28, s64
	v_add_u32_e32 v6, s77, v173
	ds_read_b128 v[180:183], v4
	ds_read_b128 v[196:199], v6
	v_add_u32_e32 v4, s79, v159
	s_addc_u32 s27, s29, s65
	v_add_u32_e32 v6, s79, v173
	ds_read_b128 v[200:203], v4
	ds_read_b128 v[204:207], v6
	v_add_u32_e32 v4, s80, v159
	s_add_u32 s26, s26, 0x100
	v_add_u32_e32 v6, s80, v173
	ds_read_b128 v[208:211], v4
	ds_read_b128 v[212:215], v6
	s_addc_u32 s27, s27, 0
	s_add_u32 s34, s93, s64
	s_addc_u32 s35, s94, s65
	s_cmpk_eq_i32 s64, 0xb00
	s_cselect_b32 s35, s63, s35
	s_cselect_b32 s34, s62, s34
	s_cselect_b32 s27, s1, s27
	s_cselect_b32 s26, s0, s26
	v_lshl_add_u64 v[6:7], v[170:171], 0, s[64:65]
	v_lshl_add_u64 v[184:185], v[6:7], 0, s[24:25]
	s_add_i32 m0, s66, 0x8000
	s_mov_b64 s[38:39], 0x30080
	ds_read_b128 v[216:219], v176
	ds_read_b128 v[220:223], v176 offset:2048
	ds_read_b128 v[224:227], v177
	ds_read_b128 v[228:231], v177 offset:2048
	ds_read_b128 v[232:235], v176 offset:4096
	ds_read_b128 v[236:239], v176 offset:6144
	ds_read_b128 v[240:243], v177 offset:4096
	ds_read_b128 v[244:247], v177 offset:6144
	global_load_lds_dwordx4 v[184:185], off
	v_lshl_add_u64 v[184:185], v[6:7], 0, s[38:39]
	s_add_i32 m0, s66, 0xa000
	s_mov_b64 s[38:39], 0x90080
	global_load_lds_dwordx4 v[184:185], off
	v_lshl_add_u64 v[184:185], v[6:7], 0, s[50:51]
	s_add_i32 m0, s66, 0xc000
	v_lshl_add_u64 v[6:7], v[6:7], 0, s[38:39]
	global_load_lds_dwordx4 v[184:185], off
	s_add_i32 m0, s66, 0xe000
	s_nop 0
	global_load_lds_dwordx4 v[6:7], off
	s_waitcnt vmcnt(8)
	s_waitcnt lgkmcnt(0)
	s_barrier
	v_mfma_f32_16x16x32_bf16 v[132:135], v[136:139], v[216:219], v[132:135]
	v_mfma_f32_16x16x32_bf16 v[132:135], v[140:143], v[224:227], v[132:135]
	v_mfma_f32_16x16x32_bf16 v[128:131], v[180:183], v[216:219], v[128:131]
	v_mfma_f32_16x16x32_bf16 v[128:131], v[196:199], v[224:227], v[128:131]
	v_mfma_f32_16x16x32_bf16 v[116:119], v[136:139], v[220:223], v[116:119]
	v_mfma_f32_16x16x32_bf16 v[116:119], v[140:143], v[228:231], v[116:119]
	v_mfma_f32_16x16x32_bf16 v[112:115], v[180:183], v[220:223], v[112:115]
	v_mfma_f32_16x16x32_bf16 v[112:115], v[196:199], v[228:231], v[112:115]
	v_mfma_f32_16x16x32_bf16 v[100:103], v[136:139], v[232:235], v[100:103]
	v_mfma_f32_16x16x32_bf16 v[100:103], v[140:143], v[240:243], v[100:103]
	v_mfma_f32_16x16x32_bf16 v[96:99], v[180:183], v[232:235], v[96:99]
	v_mfma_f32_16x16x32_bf16 v[96:99], v[196:199], v[240:243], v[96:99]
	v_mfma_f32_16x16x32_bf16 v[84:87], v[136:139], v[236:239], v[84:87]
	v_mfma_f32_16x16x32_bf16 v[84:87], v[140:143], v[244:247], v[84:87]
	v_mfma_f32_16x16x32_bf16 v[80:83], v[180:183], v[236:239], v[80:83]
	v_mfma_f32_16x16x32_bf16 v[80:83], v[196:199], v[244:247], v[80:83]
	v_mfma_f32_16x16x32_bf16 v[124:127], v[200:203], v[216:219], v[124:127]
	v_mfma_f32_16x16x32_bf16 v[124:127], v[204:207], v[224:227], v[124:127]
	v_mfma_f32_16x16x32_bf16 v[120:123], v[208:211], v[216:219], v[120:123]
	v_mfma_f32_16x16x32_bf16 v[120:123], v[212:215], v[224:227], v[120:123]
	v_mfma_f32_16x16x32_bf16 v[108:111], v[200:203], v[220:223], v[108:111]
	v_mfma_f32_16x16x32_bf16 v[108:111], v[204:207], v[228:231], v[108:111]
	v_mfma_f32_16x16x32_bf16 v[104:107], v[208:211], v[220:223], v[104:107]
	v_mfma_f32_16x16x32_bf16 v[104:107], v[212:215], v[228:231], v[104:107]
	v_mfma_f32_16x16x32_bf16 v[92:95], v[200:203], v[232:235], v[92:95]
	v_mfma_f32_16x16x32_bf16 v[92:95], v[204:207], v[240:243], v[92:95]
	v_mfma_f32_16x16x32_bf16 v[88:91], v[208:211], v[232:235], v[88:91]
	v_mfma_f32_16x16x32_bf16 v[88:91], v[212:215], v[240:243], v[88:91]
	v_mfma_f32_16x16x32_bf16 v[76:79], v[200:203], v[236:239], v[76:79]
	v_mfma_f32_16x16x32_bf16 v[76:79], v[204:207], v[244:247], v[76:79]
	v_mfma_f32_16x16x32_bf16 v[72:75], v[208:211], v[236:239], v[72:75]
	v_mfma_f32_16x16x32_bf16 v[72:75], v[212:215], v[244:247], v[72:75]
	s_barrier
	v_lshl_add_u64 v[184:185], s[34:35], 0, v[146:147]
	s_add_i32 s34, s73, s3
	s_mov_b32 m0, s34
	ds_read_b128 v[216:219], v176 offset:16384
	ds_read_b128 v[220:223], v176 offset:18432
	ds_read_b128 v[224:227], v177 offset:16384
	ds_read_b128 v[228:231], v177 offset:18432
	ds_read_b128 v[232:235], v176 offset:20480
	ds_read_b128 v[236:239], v176 offset:22528
	ds_read_b128 v[240:243], v177 offset:20480
	ds_read_b128 v[244:247], v177 offset:22528
	global_load_lds_dwordx4 v[184:185], off
	v_lshl_add_u64 v[6:7], v[184:185], 0, s[12:13]
	s_add_i32 m0, s34, 0x2000
	s_add_i32 s34, s79, s3
	global_load_lds_dwordx4 v[6:7], off
	v_lshl_add_u64 v[6:7], v[184:185], 0, s[14:15]
	s_mov_b32 m0, s34
	s_nop 0
	global_load_lds_dwordx4 v[6:7], off
	v_lshl_add_u64 v[6:7], v[184:185], 0, s[16:17]
	s_add_i32 m0, s34, 0x2000
	s_nop 0
	global_load_lds_dwordx4 v[6:7], off
	s_waitcnt vmcnt(4)
	s_waitcnt lgkmcnt(0)
	s_barrier
	v_mfma_f32_16x16x32_bf16 v[68:71], v[136:139], v[216:219], v[68:71]
	v_mfma_f32_16x16x32_bf16 v[68:71], v[140:143], v[224:227], v[68:71]
	v_mfma_f32_16x16x32_bf16 v[64:67], v[180:183], v[216:219], v[64:67]
	v_mfma_f32_16x16x32_bf16 v[64:67], v[196:199], v[224:227], v[64:67]
	v_mfma_f32_16x16x32_bf16 v[52:55], v[136:139], v[220:223], v[52:55]
	v_mfma_f32_16x16x32_bf16 v[52:55], v[140:143], v[228:231], v[52:55]
	v_mfma_f32_16x16x32_bf16 v[48:51], v[180:183], v[220:223], v[48:51]
	v_mfma_f32_16x16x32_bf16 v[48:51], v[196:199], v[228:231], v[48:51]
	v_mfma_f32_16x16x32_bf16 v[36:39], v[136:139], v[232:235], v[36:39]
	v_mfma_f32_16x16x32_bf16 v[36:39], v[140:143], v[240:243], v[36:39]
	v_mfma_f32_16x16x32_bf16 v[32:35], v[180:183], v[232:235], v[32:35]
	v_mfma_f32_16x16x32_bf16 v[32:35], v[196:199], v[240:243], v[32:35]
	v_mfma_f32_16x16x32_bf16 v[20:23], v[136:139], v[236:239], v[20:23]
	v_mfma_f32_16x16x32_bf16 v[20:23], v[140:143], v[244:247], v[20:23]
	v_mfma_f32_16x16x32_bf16 v[16:19], v[180:183], v[236:239], v[16:19]
	v_mfma_f32_16x16x32_bf16 v[16:19], v[196:199], v[244:247], v[16:19]
	v_mfma_f32_16x16x32_bf16 v[60:63], v[200:203], v[216:219], v[60:63]
	v_mfma_f32_16x16x32_bf16 v[60:63], v[204:207], v[224:227], v[60:63]
	v_mfma_f32_16x16x32_bf16 v[56:59], v[208:211], v[216:219], v[56:59]
	v_mfma_f32_16x16x32_bf16 v[56:59], v[212:215], v[224:227], v[56:59]
	v_mfma_f32_16x16x32_bf16 v[44:47], v[200:203], v[220:223], v[44:47]
	v_mfma_f32_16x16x32_bf16 v[44:47], v[204:207], v[228:231], v[44:47]
	v_mfma_f32_16x16x32_bf16 v[40:43], v[208:211], v[220:223], v[40:43]
	v_mfma_f32_16x16x32_bf16 v[40:43], v[212:215], v[228:231], v[40:43]
	v_mfma_f32_16x16x32_bf16 v[28:31], v[200:203], v[232:235], v[28:31]
	v_mfma_f32_16x16x32_bf16 v[28:31], v[204:207], v[240:243], v[28:31]
	v_mfma_f32_16x16x32_bf16 v[24:27], v[208:211], v[232:235], v[24:27]
	v_mfma_f32_16x16x32_bf16 v[24:27], v[212:215], v[240:243], v[24:27]
	v_mfma_f32_16x16x32_bf16 v[12:15], v[200:203], v[236:239], v[12:15]
	v_mfma_f32_16x16x32_bf16 v[12:15], v[204:207], v[244:247], v[12:15]
	v_mfma_f32_16x16x32_bf16 v[6:9], v[208:211], v[236:239], v[8:11]
	v_mfma_f32_16x16x32_bf16 v[6:9], v[212:215], v[244:247], v[6:9]
	s_barrier
	v_add_u32_e32 v4, s83, v159
	v_add_u32_e32 v10, s83, v173
	ds_read_b128 v[136:139], v4
	ds_read_b128 v[140:143], v10
	v_add_u32_e32 v4, s81, v159
	v_add_u32_e32 v10, s81, v173
	ds_read_b128 v[180:183], v4
	ds_read_b128 v[196:199], v10
	v_add_u32_e32 v4, s84, v159
	v_add_u32_e32 v10, s84, v173
	ds_read_b128 v[200:203], v4
	ds_read_b128 v[204:207], v10
	v_add_u32_e32 v4, s82, v159
	v_add_u32_e32 v10, s82, v173
	ds_read_b128 v[208:211], v4
	ds_read_b128 v[212:215], v10
	s_mov_b32 m0, s66
	v_lshl_add_u64 v[10:11], s[26:27], 0, v[144:145]
	ds_read_b128 v[216:219], v176 offset:32768
	ds_read_b128 v[220:223], v176 offset:34816
	ds_read_b128 v[224:227], v177 offset:32768
	ds_read_b128 v[228:231], v177 offset:34816
	ds_read_b128 v[232:235], v176 offset:36864
	ds_read_b128 v[236:239], v176 offset:38912
	ds_read_b128 v[240:243], v177 offset:36864
	ds_read_b128 v[244:247], v177 offset:38912
	global_load_lds_dwordx4 v[10:11], off
	v_lshl_add_u64 v[248:249], v[10:11], 0, s[18:19]
	s_mov_b32 m0, s67
	s_nop 0
	global_load_lds_dwordx4 v[248:249], off
	v_lshl_add_u64 v[248:249], v[10:11], 0, s[12:13]
	s_mov_b32 m0, s68
	v_lshl_add_u64 v[10:11], v[10:11], 0, s[20:21]
	global_load_lds_dwordx4 v[248:249], off
	s_mov_b32 m0, s69
	s_nop 0
	global_load_lds_dwordx4 v[10:11], off
	s_waitcnt vmcnt(8)
	s_waitcnt lgkmcnt(0)
	s_barrier
	v_mfma_f32_16x16x32_bf16 v[132:135], v[136:139], v[216:219], v[132:135]
	v_mfma_f32_16x16x32_bf16 v[132:135], v[140:143], v[224:227], v[132:135]
	v_mfma_f32_16x16x32_bf16 v[128:131], v[180:183], v[216:219], v[128:131]
	v_mfma_f32_16x16x32_bf16 v[128:131], v[196:199], v[224:227], v[128:131]
	v_mfma_f32_16x16x32_bf16 v[116:119], v[136:139], v[220:223], v[116:119]
	v_mfma_f32_16x16x32_bf16 v[116:119], v[140:143], v[228:231], v[116:119]
	v_mfma_f32_16x16x32_bf16 v[112:115], v[180:183], v[220:223], v[112:115]
	v_mfma_f32_16x16x32_bf16 v[112:115], v[196:199], v[228:231], v[112:115]
	v_mfma_f32_16x16x32_bf16 v[100:103], v[136:139], v[232:235], v[100:103]
	v_mfma_f32_16x16x32_bf16 v[100:103], v[140:143], v[240:243], v[100:103]
	v_mfma_f32_16x16x32_bf16 v[96:99], v[180:183], v[232:235], v[96:99]
	v_mfma_f32_16x16x32_bf16 v[96:99], v[196:199], v[240:243], v[96:99]
	v_mfma_f32_16x16x32_bf16 v[84:87], v[136:139], v[236:239], v[84:87]
	v_mfma_f32_16x16x32_bf16 v[84:87], v[140:143], v[244:247], v[84:87]
	v_mfma_f32_16x16x32_bf16 v[80:83], v[180:183], v[236:239], v[80:83]
	v_mfma_f32_16x16x32_bf16 v[80:83], v[196:199], v[244:247], v[80:83]
	v_mfma_f32_16x16x32_bf16 v[124:127], v[200:203], v[216:219], v[124:127]
	v_mfma_f32_16x16x32_bf16 v[124:127], v[204:207], v[224:227], v[124:127]
	v_mfma_f32_16x16x32_bf16 v[120:123], v[208:211], v[216:219], v[120:123]
	v_mfma_f32_16x16x32_bf16 v[120:123], v[212:215], v[224:227], v[120:123]
	v_mfma_f32_16x16x32_bf16 v[108:111], v[200:203], v[220:223], v[108:111]
	v_mfma_f32_16x16x32_bf16 v[108:111], v[204:207], v[228:231], v[108:111]
	v_mfma_f32_16x16x32_bf16 v[104:107], v[208:211], v[220:223], v[104:107]
	v_mfma_f32_16x16x32_bf16 v[104:107], v[212:215], v[228:231], v[104:107]
	v_mfma_f32_16x16x32_bf16 v[92:95], v[200:203], v[232:235], v[92:95]
	v_mfma_f32_16x16x32_bf16 v[92:95], v[204:207], v[240:243], v[92:95]
	v_mfma_f32_16x16x32_bf16 v[88:91], v[208:211], v[232:235], v[88:91]
	v_mfma_f32_16x16x32_bf16 v[88:91], v[212:215], v[240:243], v[88:91]
	v_mfma_f32_16x16x32_bf16 v[76:79], v[200:203], v[236:239], v[76:79]
	v_mfma_f32_16x16x32_bf16 v[76:79], v[204:207], v[244:247], v[76:79]
	v_mfma_f32_16x16x32_bf16 v[72:75], v[208:211], v[236:239], v[72:75]
	v_mfma_f32_16x16x32_bf16 v[72:75], v[212:215], v[244:247], v[72:75]
	s_barrier
	s_add_i32 s26, s83, s3
	v_lshl_add_u64 v[10:11], v[184:185], 0, s[24:25]
	s_mov_b32 m0, s26
	ds_read_b128 v[216:219], v176 offset:49152
	ds_read_b128 v[220:223], v176 offset:51200
	ds_read_b128 v[224:227], v177 offset:49152
	ds_read_b128 v[228:231], v177 offset:51200
	ds_read_b128 v[232:235], v176 offset:53248
	ds_read_b128 v[236:239], v176 offset:55296
	ds_read_b128 v[240:243], v177 offset:53248
	ds_read_b128 v[244:247], v177 offset:55296
	global_load_lds_dwordx4 v[10:11], off
	v_lshl_add_u64 v[10:11], v[184:185], 0, s[50:51]
	s_add_i32 m0, s26, 0x2000
	s_add_i32 s26, s84, s3
	global_load_lds_dwordx4 v[10:11], off
	v_lshl_add_u64 v[10:11], v[184:185], 0, s[52:53]
	s_mov_b32 m0, s26
	s_nop 0
	global_load_lds_dwordx4 v[10:11], off
	v_lshl_add_u64 v[10:11], v[184:185], 0, s[54:55]
	s_add_i32 m0, s26, 0x2000
	s_nop 0
	global_load_lds_dwordx4 v[10:11], off
	s_waitcnt vmcnt(4)
	s_waitcnt lgkmcnt(0)
	s_barrier
	v_mfma_f32_16x16x32_bf16 v[68:71], v[136:139], v[216:219], v[68:71]
	v_mfma_f32_16x16x32_bf16 v[68:71], v[140:143], v[224:227], v[68:71]
	v_mfma_f32_16x16x32_bf16 v[64:67], v[180:183], v[216:219], v[64:67]
	v_mfma_f32_16x16x32_bf16 v[64:67], v[196:199], v[224:227], v[64:67]
	v_mfma_f32_16x16x32_bf16 v[52:55], v[136:139], v[220:223], v[52:55]
	v_mfma_f32_16x16x32_bf16 v[52:55], v[140:143], v[228:231], v[52:55]
	v_mfma_f32_16x16x32_bf16 v[48:51], v[180:183], v[220:223], v[48:51]
	v_mfma_f32_16x16x32_bf16 v[48:51], v[196:199], v[228:231], v[48:51]
	v_mfma_f32_16x16x32_bf16 v[36:39], v[136:139], v[232:235], v[36:39]
	v_mfma_f32_16x16x32_bf16 v[36:39], v[140:143], v[240:243], v[36:39]
	v_mfma_f32_16x16x32_bf16 v[32:35], v[180:183], v[232:235], v[32:35]
	v_mfma_f32_16x16x32_bf16 v[32:35], v[196:199], v[240:243], v[32:35]
	v_mfma_f32_16x16x32_bf16 v[20:23], v[136:139], v[236:239], v[20:23]
	v_mfma_f32_16x16x32_bf16 v[20:23], v[140:143], v[244:247], v[20:23]
	v_mfma_f32_16x16x32_bf16 v[16:19], v[180:183], v[236:239], v[16:19]
	v_mfma_f32_16x16x32_bf16 v[16:19], v[196:199], v[244:247], v[16:19]
	v_mfma_f32_16x16x32_bf16 v[60:63], v[200:203], v[216:219], v[60:63]
	v_mfma_f32_16x16x32_bf16 v[60:63], v[204:207], v[224:227], v[60:63]
	v_mfma_f32_16x16x32_bf16 v[56:59], v[208:211], v[216:219], v[56:59]
	v_mfma_f32_16x16x32_bf16 v[56:59], v[212:215], v[224:227], v[56:59]
	v_mfma_f32_16x16x32_bf16 v[44:47], v[200:203], v[220:223], v[44:47]
	v_mfma_f32_16x16x32_bf16 v[44:47], v[204:207], v[228:231], v[44:47]
	v_mfma_f32_16x16x32_bf16 v[40:43], v[208:211], v[220:223], v[40:43]
	v_mfma_f32_16x16x32_bf16 v[40:43], v[212:215], v[228:231], v[40:43]
	v_mfma_f32_16x16x32_bf16 v[28:31], v[200:203], v[232:235], v[28:31]
	v_mfma_f32_16x16x32_bf16 v[28:31], v[204:207], v[240:243], v[28:31]
	v_mfma_f32_16x16x32_bf16 v[24:27], v[208:211], v[232:235], v[24:27]
	v_mfma_f32_16x16x32_bf16 v[24:27], v[212:215], v[240:243], v[24:27]
	v_mfma_f32_16x16x32_bf16 v[10:13], v[200:203], v[236:239], v[12:15]
	v_mfma_f32_16x16x32_bf16 v[12:15], v[204:207], v[244:247], v[10:13]
	v_mfma_f32_16x16x32_bf16 v[6:9], v[208:211], v[236:239], v[6:9]
	v_mfma_f32_16x16x32_bf16 v[8:11], v[212:215], v[244:247], v[6:9]
	s_barrier
	s_add_i32 s95, s95, 2
	s_add_u32 s64, s64, 0x100
	s_addc_u32 s65, s65, 0
	s_cmp_gt_u32 s95, 21
	s_cbranch_scc1 .LBB0_782

.LBB0_973:
	v_add_u32_e32 v133, s72, v163
	v_add_u32_e32 v140, s72, v164
	ds_read_b128 v[136:139], v133
	ds_read_b128 v[148:151], v140
	v_add_u32_e32 v133, s73, v163
	s_add_u32 s70, s28, s26
	v_add_u32_e32 v140, s73, v164
	s_waitcnt lgkmcnt(0)
	ds_read_b128 v[152:155], v133
	ds_read_b128 v[174:177], v140
	v_add_u32_e32 v133, s77, v163
	s_addc_u32 s71, s29, s27
	v_add_u32_e32 v140, s77, v164
	ds_read_b128 v[178:181], v133
	ds_read_b128 v[182:185], v140
	v_add_u32_e32 v133, s79, v163
	s_add_u32 s70, s70, 0x100
	v_add_u32_e32 v140, s79, v164
	ds_read_b128 v[196:199], v133
	ds_read_b128 v[200:203], v140
	s_addc_u32 s71, s71, 0
	s_add_u32 s86, s65, s26
	s_addc_u32 s87, s85, s27
	s_cmpk_eq_i32 s26, 0x700
	s_cselect_b32 s87, s61, s87
	s_cselect_b32 s86, s88, s86
	s_cselect_b32 s71, s54, s71
	s_cselect_b32 s70, s63, s70
	v_lshl_add_u64 v[140:141], v[134:135], 0, s[26:27]
	v_lshl_add_u64 v[160:161], v[140:141], 0, s[36:37]
	s_add_i32 m0, s5, 0x8000
	s_mov_b64 s[90:91], 0x20080
	ds_read_b128 v[204:207], v166
	ds_read_b128 v[208:211], v166 offset:2048
	ds_read_b128 v[212:215], v167
	ds_read_b128 v[216:219], v167 offset:2048
	ds_read_b128 v[220:223], v166 offset:4096
	ds_read_b128 v[224:227], v166 offset:6144
	ds_read_b128 v[228:231], v167 offset:4096
	ds_read_b128 v[232:235], v167 offset:6144
	global_load_lds_dwordx4 v[160:161], off
	v_lshl_add_u64 v[160:161], v[140:141], 0, s[90:91]
	s_add_i32 m0, s5, 0xa000
	s_mov_b64 s[90:91], 0x60080
	global_load_lds_dwordx4 v[160:161], off
	v_lshl_add_u64 v[160:161], v[140:141], 0, s[44:45]
	s_add_i32 m0, s5, 0xc000
	v_lshl_add_u64 v[140:141], v[140:141], 0, s[90:91]
	global_load_lds_dwordx4 v[160:161], off
	s_add_i32 m0, s5, 0xe000
	s_nop 0
	global_load_lds_dwordx4 v[140:141], off
	s_waitcnt vmcnt(8)
	s_waitcnt lgkmcnt(0)
	s_barrier
	v_mfma_f32_16x16x32_bf16 v[8:11], v[136:139], v[204:207], v[8:11]
	v_mfma_f32_16x16x32_bf16 v[8:11], v[148:151], v[212:215], v[8:11]
	v_mfma_f32_16x16x32_bf16 v[4:7], v[152:155], v[204:207], v[4:7]
	v_mfma_f32_16x16x32_bf16 v[4:7], v[174:177], v[212:215], v[4:7]
	v_mfma_f32_16x16x32_bf16 v[12:15], v[136:139], v[208:211], v[12:15]
	v_mfma_f32_16x16x32_bf16 v[12:15], v[148:151], v[216:219], v[12:15]
	v_mfma_f32_16x16x32_bf16 v[16:19], v[152:155], v[208:211], v[16:19]
	v_mfma_f32_16x16x32_bf16 v[16:19], v[174:177], v[216:219], v[16:19]
	v_mfma_f32_16x16x32_bf16 v[44:47], v[136:139], v[220:223], v[44:47]
	v_mfma_f32_16x16x32_bf16 v[44:47], v[148:151], v[228:231], v[44:47]
	v_mfma_f32_16x16x32_bf16 v[36:39], v[152:155], v[220:223], v[36:39]
	v_mfma_f32_16x16x32_bf16 v[36:39], v[174:177], v[228:231], v[36:39]
	v_mfma_f32_16x16x32_bf16 v[20:23], v[136:139], v[224:227], v[20:23]
	v_mfma_f32_16x16x32_bf16 v[20:23], v[148:151], v[232:235], v[20:23]
	v_mfma_f32_16x16x32_bf16 v[24:27], v[152:155], v[224:227], v[24:27]
	v_mfma_f32_16x16x32_bf16 v[24:27], v[174:177], v[232:235], v[24:27]
	v_mfma_f32_16x16x32_bf16 v[32:35], v[178:181], v[204:207], v[32:35]
	v_mfma_f32_16x16x32_bf16 v[32:35], v[182:185], v[212:215], v[32:35]
	v_mfma_f32_16x16x32_bf16 v[28:31], v[196:199], v[204:207], v[28:31]
	v_mfma_f32_16x16x32_bf16 v[28:31], v[200:203], v[212:215], v[28:31]
	v_mfma_f32_16x16x32_bf16 v[40:43], v[178:181], v[208:211], v[40:43]
	v_mfma_f32_16x16x32_bf16 v[40:43], v[182:185], v[216:219], v[40:43]
	v_mfma_f32_16x16x32_bf16 v[52:55], v[196:199], v[208:211], v[52:55]
	v_mfma_f32_16x16x32_bf16 v[52:55], v[200:203], v[216:219], v[52:55]
	v_mfma_f32_16x16x32_bf16 v[48:51], v[178:181], v[220:223], v[48:51]
	v_mfma_f32_16x16x32_bf16 v[48:51], v[182:185], v[228:231], v[48:51]
	v_mfma_f32_16x16x32_bf16 v[60:63], v[196:199], v[220:223], v[60:63]
	v_mfma_f32_16x16x32_bf16 v[60:63], v[200:203], v[228:231], v[60:63]
	v_mfma_f32_16x16x32_bf16 v[56:59], v[178:181], v[224:227], v[56:59]
	v_mfma_f32_16x16x32_bf16 v[56:59], v[182:185], v[232:235], v[56:59]
	v_mfma_f32_16x16x32_bf16 v[64:67], v[196:199], v[224:227], v[64:67]
	v_mfma_f32_16x16x32_bf16 v[64:67], v[200:203], v[232:235], v[64:67]
	s_barrier
	v_lshl_add_u64 v[140:141], s[86:87], 0, v[158:159]
	s_add_i32 s86, s72, s34
	s_mov_b32 m0, s86
	ds_read_b128 v[204:207], v166 offset:16384
	ds_read_b128 v[208:211], v166 offset:18432
	ds_read_b128 v[212:215], v167 offset:16384
	ds_read_b128 v[216:219], v167 offset:18432
	ds_read_b128 v[220:223], v166 offset:20480
	ds_read_b128 v[224:227], v166 offset:22528
	ds_read_b128 v[228:231], v167 offset:20480
	ds_read_b128 v[232:235], v167 offset:22528
	global_load_lds_dwordx4 v[140:141], off
	v_lshl_add_u64 v[160:161], v[140:141], 0, s[18:19]
	s_add_i32 m0, s86, 0x2000
	s_mov_b64 s[86:87], 0x10000
	global_load_lds_dwordx4 v[160:161], off
	v_lshl_add_u64 v[160:161], v[140:141], 0, s[86:87]
	s_add_i32 s86, s77, s34
	s_mov_b32 m0, s86
	s_nop 0
	global_load_lds_dwordx4 v[160:161], off
	v_lshl_add_u64 v[160:161], v[140:141], 0, s[20:21]
	s_add_i32 m0, s86, 0x2000
	s_nop 0
	global_load_lds_dwordx4 v[160:161], off
	s_waitcnt vmcnt(4)
	s_waitcnt lgkmcnt(0)
	s_barrier
	v_mfma_f32_16x16x32_bf16 v[68:71], v[136:139], v[204:207], v[68:71]
	v_mfma_f32_16x16x32_bf16 v[68:71], v[148:151], v[212:215], v[68:71]
	v_mfma_f32_16x16x32_bf16 v[72:75], v[152:155], v[204:207], v[72:75]
	v_mfma_f32_16x16x32_bf16 v[72:75], v[174:177], v[212:215], v[72:75]
	v_mfma_f32_16x16x32_bf16 v[92:95], v[136:139], v[208:211], v[92:95]
	v_mfma_f32_16x16x32_bf16 v[92:95], v[148:151], v[216:219], v[92:95]
	v_mfma_f32_16x16x32_bf16 v[84:87], v[152:155], v[208:211], v[84:87]
	v_mfma_f32_16x16x32_bf16 v[84:87], v[174:177], v[216:219], v[84:87]
	v_mfma_f32_16x16x32_bf16 v[76:79], v[136:139], v[220:223], v[76:79]
	v_mfma_f32_16x16x32_bf16 v[76:79], v[148:151], v[228:231], v[76:79]
	v_mfma_f32_16x16x32_bf16 v[80:83], v[152:155], v[220:223], v[80:83]
	v_mfma_f32_16x16x32_bf16 v[80:83], v[174:177], v[228:231], v[80:83]
	v_mfma_f32_16x16x32_bf16 v[116:119], v[136:139], v[224:227], v[116:119]
	v_mfma_f32_16x16x32_bf16 v[116:119], v[148:151], v[232:235], v[116:119]
	v_mfma_f32_16x16x32_bf16 v[108:111], v[152:155], v[224:227], v[108:111]
	v_mfma_f32_16x16x32_bf16 v[108:111], v[174:177], v[232:235], v[108:111]
	v_mfma_f32_16x16x32_bf16 v[88:91], v[178:181], v[204:207], v[88:91]
	v_mfma_f32_16x16x32_bf16 v[88:91], v[182:185], v[212:215], v[88:91]
	v_mfma_f32_16x16x32_bf16 v[100:103], v[196:199], v[204:207], v[100:103]
	v_mfma_f32_16x16x32_bf16 v[100:103], v[200:203], v[212:215], v[100:103]
	v_mfma_f32_16x16x32_bf16 v[96:99], v[178:181], v[208:211], v[96:99]
	v_mfma_f32_16x16x32_bf16 v[96:99], v[182:185], v[216:219], v[96:99]
	v_mfma_f32_16x16x32_bf16 v[104:107], v[196:199], v[208:211], v[104:107]
	v_mfma_f32_16x16x32_bf16 v[104:107], v[200:203], v[216:219], v[104:107]
	v_mfma_f32_16x16x32_bf16 v[112:115], v[178:181], v[220:223], v[112:115]
	v_mfma_f32_16x16x32_bf16 v[112:115], v[182:185], v[228:231], v[112:115]
	v_mfma_f32_16x16x32_bf16 v[124:127], v[196:199], v[220:223], v[124:127]
	v_mfma_f32_16x16x32_bf16 v[124:127], v[200:203], v[228:231], v[124:127]
	v_mfma_f32_16x16x32_bf16 v[120:123], v[178:181], v[224:227], v[120:123]
	v_mfma_f32_16x16x32_bf16 v[120:123], v[182:185], v[232:235], v[120:123]
	v_mfma_f32_16x16x32_bf16 v[128:131], v[196:199], v[224:227], v[128:131]
	v_mfma_f32_16x16x32_bf16 v[128:131], v[200:203], v[232:235], v[128:131]
	s_barrier
	v_add_u32_e32 v133, s82, v163
	v_add_u32_e32 v148, s82, v164
	ds_read_b128 v[136:139], v133
	ds_read_b128 v[148:151], v148
	v_add_u32_e32 v133, s80, v163
	v_add_u32_e32 v160, s80, v164
	ds_read_b128 v[152:155], v133
	ds_read_b128 v[174:177], v160
	v_add_u32_e32 v133, s83, v163
	v_add_u32_e32 v160, s83, v164
	ds_read_b128 v[178:181], v133
	ds_read_b128 v[182:185], v160
	v_add_u32_e32 v133, s81, v163
	v_add_u32_e32 v160, s81, v164
	ds_read_b128 v[196:199], v133
	ds_read_b128 v[200:203], v160
	s_mov_b32 m0, s5
	v_lshl_add_u64 v[160:161], s[70:71], 0, v[0:1]
	s_mov_b64 s[70:71], 0x20000
	ds_read_b128 v[204:207], v166 offset:32768
	ds_read_b128 v[208:211], v166 offset:34816
	ds_read_b128 v[212:215], v167 offset:32768
	ds_read_b128 v[216:219], v167 offset:34816
	ds_read_b128 v[220:223], v166 offset:36864
	ds_read_b128 v[224:227], v166 offset:38912
	ds_read_b128 v[228:231], v167 offset:36864
	ds_read_b128 v[232:235], v167 offset:38912
	global_load_lds_dwordx4 v[160:161], off
	v_lshl_add_u64 v[170:171], v[160:161], 0, s[70:71]
	s_mov_b32 m0, s17
	s_nop 0
	global_load_lds_dwordx4 v[170:171], off
	v_lshl_add_u64 v[170:171], v[160:161], 0, s[18:19]
	s_mov_b32 m0, s35
	v_lshl_add_u64 v[160:161], v[160:161], 0, s[22:23]
	global_load_lds_dwordx4 v[170:171], off
	s_mov_b32 m0, s38
	s_nop 0
	global_load_lds_dwordx4 v[160:161], off
	s_waitcnt vmcnt(8)
	s_waitcnt lgkmcnt(0)
	s_barrier
	v_mfma_f32_16x16x32_bf16 v[8:11], v[136:139], v[204:207], v[8:11]
	v_mfma_f32_16x16x32_bf16 v[8:11], v[148:151], v[212:215], v[8:11]
	v_mfma_f32_16x16x32_bf16 v[4:7], v[152:155], v[204:207], v[4:7]
	v_mfma_f32_16x16x32_bf16 v[4:7], v[174:177], v[212:215], v[4:7]
	v_mfma_f32_16x16x32_bf16 v[12:15], v[136:139], v[208:211], v[12:15]
	v_mfma_f32_16x16x32_bf16 v[12:15], v[148:151], v[216:219], v[12:15]
	v_mfma_f32_16x16x32_bf16 v[16:19], v[152:155], v[208:211], v[16:19]
	v_mfma_f32_16x16x32_bf16 v[16:19], v[174:177], v[216:219], v[16:19]
	v_mfma_f32_16x16x32_bf16 v[44:47], v[136:139], v[220:223], v[44:47]
	v_mfma_f32_16x16x32_bf16 v[44:47], v[148:151], v[228:231], v[44:47]
	v_mfma_f32_16x16x32_bf16 v[36:39], v[152:155], v[220:223], v[36:39]
	v_mfma_f32_16x16x32_bf16 v[36:39], v[174:177], v[228:231], v[36:39]
	v_mfma_f32_16x16x32_bf16 v[20:23], v[136:139], v[224:227], v[20:23]
	v_mfma_f32_16x16x32_bf16 v[20:23], v[148:151], v[232:235], v[20:23]
	v_mfma_f32_16x16x32_bf16 v[24:27], v[152:155], v[224:227], v[24:27]
	v_mfma_f32_16x16x32_bf16 v[24:27], v[174:177], v[232:235], v[24:27]
	v_mfma_f32_16x16x32_bf16 v[32:35], v[178:181], v[204:207], v[32:35]
	v_mfma_f32_16x16x32_bf16 v[32:35], v[182:185], v[212:215], v[32:35]
	v_mfma_f32_16x16x32_bf16 v[28:31], v[196:199], v[204:207], v[28:31]
	v_mfma_f32_16x16x32_bf16 v[28:31], v[200:203], v[212:215], v[28:31]
	v_mfma_f32_16x16x32_bf16 v[40:43], v[178:181], v[208:211], v[40:43]
	v_mfma_f32_16x16x32_bf16 v[40:43], v[182:185], v[216:219], v[40:43]
	v_mfma_f32_16x16x32_bf16 v[52:55], v[196:199], v[208:211], v[52:55]
	v_mfma_f32_16x16x32_bf16 v[52:55], v[200:203], v[216:219], v[52:55]
	v_mfma_f32_16x16x32_bf16 v[48:51], v[178:181], v[220:223], v[48:51]
	v_mfma_f32_16x16x32_bf16 v[48:51], v[182:185], v[228:231], v[48:51]
	v_mfma_f32_16x16x32_bf16 v[60:63], v[196:199], v[220:223], v[60:63]
	v_mfma_f32_16x16x32_bf16 v[60:63], v[200:203], v[228:231], v[60:63]
	v_mfma_f32_16x16x32_bf16 v[56:59], v[178:181], v[224:227], v[56:59]
	v_mfma_f32_16x16x32_bf16 v[56:59], v[182:185], v[232:235], v[56:59]
	v_mfma_f32_16x16x32_bf16 v[64:67], v[196:199], v[224:227], v[64:67]
	v_mfma_f32_16x16x32_bf16 v[64:67], v[200:203], v[232:235], v[64:67]
	s_barrier
	s_add_i32 s70, s82, s34
	v_lshl_add_u64 v[160:161], v[140:141], 0, s[36:37]
	s_mov_b32 m0, s70
	ds_read_b128 v[204:207], v166 offset:49152
	ds_read_b128 v[208:211], v166 offset:51200
	ds_read_b128 v[212:215], v167 offset:49152
	ds_read_b128 v[216:219], v167 offset:51200
	ds_read_b128 v[220:223], v166 offset:53248
	ds_read_b128 v[224:227], v166 offset:55296
	ds_read_b128 v[228:231], v167 offset:53248
	ds_read_b128 v[232:235], v167 offset:55296
	global_load_lds_dwordx4 v[160:161], off
	v_lshl_add_u64 v[160:161], v[140:141], 0, s[44:45]
	s_add_i32 m0, s70, 0x2000
	s_add_i32 s70, s83, s34
	global_load_lds_dwordx4 v[160:161], off
	v_lshl_add_u64 v[160:161], v[140:141], 0, s[46:47]
	s_mov_b32 m0, s70
	v_lshl_add_u64 v[140:141], v[140:141], 0, s[50:51]
	global_load_lds_dwordx4 v[160:161], off
	s_add_i32 m0, s70, 0x2000
	s_nop 0
	global_load_lds_dwordx4 v[140:141], off
	s_waitcnt vmcnt(4)
	s_waitcnt lgkmcnt(0)
	s_barrier
	v_mfma_f32_16x16x32_bf16 v[68:71], v[136:139], v[204:207], v[68:71]
	v_mfma_f32_16x16x32_bf16 v[68:71], v[148:151], v[212:215], v[68:71]
	v_mfma_f32_16x16x32_bf16 v[72:75], v[152:155], v[204:207], v[72:75]
	v_mfma_f32_16x16x32_bf16 v[72:75], v[174:177], v[212:215], v[72:75]
	v_mfma_f32_16x16x32_bf16 v[92:95], v[136:139], v[208:211], v[92:95]
	v_mfma_f32_16x16x32_bf16 v[92:95], v[148:151], v[216:219], v[92:95]
	v_mfma_f32_16x16x32_bf16 v[84:87], v[152:155], v[208:211], v[84:87]
	v_mfma_f32_16x16x32_bf16 v[84:87], v[174:177], v[216:219], v[84:87]
	v_mfma_f32_16x16x32_bf16 v[76:79], v[136:139], v[220:223], v[76:79]
	v_mfma_f32_16x16x32_bf16 v[76:79], v[148:151], v[228:231], v[76:79]
	v_mfma_f32_16x16x32_bf16 v[80:83], v[152:155], v[220:223], v[80:83]
	v_mfma_f32_16x16x32_bf16 v[80:83], v[174:177], v[228:231], v[80:83]
	v_mfma_f32_16x16x32_bf16 v[116:119], v[136:139], v[224:227], v[116:119]
	v_mfma_f32_16x16x32_bf16 v[116:119], v[148:151], v[232:235], v[116:119]
	v_mfma_f32_16x16x32_bf16 v[108:111], v[152:155], v[224:227], v[108:111]
	v_mfma_f32_16x16x32_bf16 v[108:111], v[174:177], v[232:235], v[108:111]
	v_mfma_f32_16x16x32_bf16 v[88:91], v[178:181], v[204:207], v[88:91]
	v_mfma_f32_16x16x32_bf16 v[88:91], v[182:185], v[212:215], v[88:91]
	v_mfma_f32_16x16x32_bf16 v[100:103], v[196:199], v[204:207], v[100:103]
	v_mfma_f32_16x16x32_bf16 v[100:103], v[200:203], v[212:215], v[100:103]
	v_mfma_f32_16x16x32_bf16 v[96:99], v[178:181], v[208:211], v[96:99]
	v_mfma_f32_16x16x32_bf16 v[96:99], v[182:185], v[216:219], v[96:99]
	v_mfma_f32_16x16x32_bf16 v[104:107], v[196:199], v[208:211], v[104:107]
	v_mfma_f32_16x16x32_bf16 v[104:107], v[200:203], v[216:219], v[104:107]
	v_mfma_f32_16x16x32_bf16 v[112:115], v[178:181], v[220:223], v[112:115]
	v_mfma_f32_16x16x32_bf16 v[112:115], v[182:185], v[228:231], v[112:115]
	v_mfma_f32_16x16x32_bf16 v[124:127], v[196:199], v[220:223], v[124:127]
	v_mfma_f32_16x16x32_bf16 v[124:127], v[200:203], v[228:231], v[124:127]
	v_mfma_f32_16x16x32_bf16 v[120:123], v[178:181], v[224:227], v[120:123]
	v_mfma_f32_16x16x32_bf16 v[120:123], v[182:185], v[232:235], v[120:123]
	v_mfma_f32_16x16x32_bf16 v[128:131], v[196:199], v[224:227], v[128:131]
	v_mfma_f32_16x16x32_bf16 v[128:131], v[200:203], v[232:235], v[128:131]
	s_barrier
	s_add_i32 s89, s89, 2
	s_add_u32 s26, s26, 0x100
	s_addc_u32 s27, s27, 0
	s_cmp_gt_u32 s89, 13
	s_cbranch_scc0 .LBB0_973
	s_and_b64 vcc, exec, s[52:53]
	s_cbranch_vccz .LBB0_976
	s_barrier

.LBB0_1134:
	s_ashr_i32 s57, s56, 31
	s_lshl_b64 s[60:61], s[56:57], 19
	s_add_u32 s60, s42, s60
	s_addc_u32 s61, s43, s61
	s_and_b64 s[62:63], s[10:11], exec
	s_cselect_b32 s57, s61, s27
	s_cselect_b32 s79, s60, s26
	s_ashr_i32 s59, s58, 31
	s_lshl_b64 s[62:63], s[58:59], 19
	v_readlane_b32 s70, v254, 7
	v_readlane_b32 s71, v254, 8
	s_add_u32 s62, s70, s62
	s_addc_u32 s63, s71, s63
	s_and_b64 s[70:71], s[10:11], exec
	s_cselect_b32 s59, s63, s69
	s_cselect_b32 s80, s62, s68
	s_add_u32 s81, s68, 0x100
	v_lshl_add_u64 v[138:139], s[26:27], 0, v[132:133]
	s_addc_u32 s82, s69, 0
	s_mov_b32 s83, -2
	s_mov_b64 s[68:69], 0
	ds_read_b128 v[168:171], v145
	ds_read_b128 v[174:177], v146
	ds_read_b128 v[178:181], v147
	ds_read_b128 v[182:185], v148
	ds_read_b128 v[194:197], v149
	ds_read_b128 v[198:201], v150
	ds_read_b128 v[202:205], v151
	ds_read_b128 v[206:209], v152
	s_add_u32 s70, s26, s68
	s_addc_u32 s71, s27, s69
	s_add_u32 s70, s70, 0x100
	s_addc_u32 s71, s71, 0
	s_add_u32 s84, s81, s68
	s_addc_u32 s85, s82, s69
	s_cmpk_eq_i32 s68, 0x700
	s_cselect_b32 s85, s59, s85
	s_cselect_b32 s84, s80, s84
	s_cselect_b32 s71, s57, s71
	s_cselect_b32 s70, s79, s70
	v_lshl_add_u64 v[140:141], v[138:139], 0, s[68:69]
	v_lshl_add_u64 v[242:243], v[140:141], 0, s[22:23]
	s_add_i32 m0, s34, 0x8000
	s_mov_b64 s[86:87], 0x20080
	ds_read_b128 v[210:213], v153
	ds_read_b128 v[214:217], v153 offset:2048
	ds_read_b128 v[218:221], v154
	ds_read_b128 v[222:225], v154 offset:2048
	ds_read_b128 v[226:229], v153 offset:4096
	ds_read_b128 v[230:233], v153 offset:6144
	ds_read_b128 v[234:237], v154 offset:4096
	ds_read_b128 v[238:241], v154 offset:6144
	global_load_lds_dwordx4 v[242:243], off
	v_lshl_add_u64 v[242:243], v[140:141], 0, s[86:87]
	s_add_i32 m0, s34, 0xa000
	s_mov_b64 s[86:87], 0x60080
	global_load_lds_dwordx4 v[242:243], off
	v_lshl_add_u64 v[242:243], v[140:141], 0, s[24:25]
	s_add_i32 m0, s34, 0xc000
	v_lshl_add_u64 v[140:141], v[140:141], 0, s[86:87]
	global_load_lds_dwordx4 v[242:243], off
	s_add_i32 m0, s34, 0xe000
	s_nop 0
	global_load_lds_dwordx4 v[140:141], off
	s_waitcnt lgkmcnt(0)
	s_barrier
	v_mfma_f32_16x16x32_bf16 v[128:131], v[168:171], v[210:213], 0
	v_mfma_f32_16x16x32_bf16 v[128:131], v[174:177], v[218:221], v[128:131]
	v_mfma_f32_16x16x32_bf16 v[124:127], v[178:181], v[210:213], 0
	v_mfma_f32_16x16x32_bf16 v[124:127], v[182:185], v[218:221], v[124:127]
	v_mfma_f32_16x16x32_bf16 v[112:115], v[168:171], v[214:217], 0
	v_mfma_f32_16x16x32_bf16 v[112:115], v[174:177], v[222:225], v[112:115]
	v_mfma_f32_16x16x32_bf16 v[108:111], v[178:181], v[214:217], 0
	v_mfma_f32_16x16x32_bf16 v[108:111], v[182:185], v[222:225], v[108:111]
	v_mfma_f32_16x16x32_bf16 v[96:99], v[168:171], v[226:229], 0
	v_mfma_f32_16x16x32_bf16 v[96:99], v[174:177], v[234:237], v[96:99]
	v_mfma_f32_16x16x32_bf16 v[92:95], v[178:181], v[226:229], 0
	v_mfma_f32_16x16x32_bf16 v[92:95], v[182:185], v[234:237], v[92:95]
	v_mfma_f32_16x16x32_bf16 v[80:83], v[168:171], v[230:233], 0
	v_mfma_f32_16x16x32_bf16 v[80:83], v[174:177], v[238:241], v[80:83]
	v_mfma_f32_16x16x32_bf16 v[76:79], v[178:181], v[230:233], 0
	v_mfma_f32_16x16x32_bf16 v[76:79], v[182:185], v[238:241], v[76:79]
	v_mfma_f32_16x16x32_bf16 v[120:123], v[194:197], v[210:213], 0
	v_mfma_f32_16x16x32_bf16 v[120:123], v[198:201], v[218:221], v[120:123]
	v_mfma_f32_16x16x32_bf16 v[116:119], v[202:205], v[210:213], 0
	v_mfma_f32_16x16x32_bf16 v[116:119], v[206:209], v[218:221], v[116:119]
	v_mfma_f32_16x16x32_bf16 v[104:107], v[194:197], v[214:217], 0
	v_mfma_f32_16x16x32_bf16 v[104:107], v[198:201], v[222:225], v[104:107]
	v_mfma_f32_16x16x32_bf16 v[100:103], v[202:205], v[214:217], 0
	v_mfma_f32_16x16x32_bf16 v[100:103], v[206:209], v[222:225], v[100:103]
	v_mfma_f32_16x16x32_bf16 v[88:91], v[194:197], v[226:229], 0
	v_mfma_f32_16x16x32_bf16 v[88:91], v[198:201], v[234:237], v[88:91]
	v_mfma_f32_16x16x32_bf16 v[84:87], v[202:205], v[226:229], 0
	v_mfma_f32_16x16x32_bf16 v[84:87], v[206:209], v[234:237], v[84:87]
	v_mfma_f32_16x16x32_bf16 v[72:75], v[194:197], v[230:233], 0
	v_mfma_f32_16x16x32_bf16 v[72:75], v[198:201], v[238:241], v[72:75]
	v_mfma_f32_16x16x32_bf16 v[68:71], v[202:205], v[230:233], 0
	v_mfma_f32_16x16x32_bf16 v[68:71], v[206:209], v[238:241], v[68:71]
	s_barrier
	v_lshl_add_u64 v[140:141], s[84:85], 0, v[158:159]
	s_add_i32 s84, s67, s3
	s_mov_b32 m0, s84
	ds_read_b128 v[210:213], v153 offset:16384
	ds_read_b128 v[214:217], v153 offset:18432
	ds_read_b128 v[218:221], v154 offset:16384
	ds_read_b128 v[222:225], v154 offset:18432
	ds_read_b128 v[226:229], v153 offset:20480
	ds_read_b128 v[230:233], v153 offset:22528
	ds_read_b128 v[234:237], v154 offset:20480
	ds_read_b128 v[238:241], v154 offset:22528
	global_load_lds_dwordx4 v[140:141], off
	v_lshl_add_u64 v[242:243], v[140:141], 0, s[0:1]
	s_add_i32 m0, s84, 0x2000
	s_add_i32 s84, s72, s3
	global_load_lds_dwordx4 v[242:243], off
	v_lshl_add_u64 v[242:243], v[140:141], 0, s[12:13]
	s_mov_b32 m0, s84
	s_nop 0
	global_load_lds_dwordx4 v[242:243], off
	v_lshl_add_u64 v[242:243], v[140:141], 0, s[14:15]
	s_add_i32 m0, s84, 0x2000
	s_nop 0
	global_load_lds_dwordx4 v[242:243], off
	s_waitcnt vmcnt(4)
	s_waitcnt lgkmcnt(0)
	s_barrier
	v_mfma_f32_16x16x32_bf16 v[64:67], v[168:171], v[210:213], 0
	v_mfma_f32_16x16x32_bf16 v[64:67], v[174:177], v[218:221], v[64:67]
	v_mfma_f32_16x16x32_bf16 v[60:63], v[178:181], v[210:213], 0
	v_mfma_f32_16x16x32_bf16 v[60:63], v[182:185], v[218:221], v[60:63]
	v_mfma_f32_16x16x32_bf16 v[48:51], v[168:171], v[214:217], 0
	v_mfma_f32_16x16x32_bf16 v[48:51], v[174:177], v[222:225], v[48:51]
	v_mfma_f32_16x16x32_bf16 v[44:47], v[178:181], v[214:217], 0
	v_mfma_f32_16x16x32_bf16 v[44:47], v[182:185], v[222:225], v[44:47]
	v_mfma_f32_16x16x32_bf16 v[32:35], v[168:171], v[226:229], 0
	v_mfma_f32_16x16x32_bf16 v[32:35], v[174:177], v[234:237], v[32:35]
	v_mfma_f32_16x16x32_bf16 v[28:31], v[178:181], v[226:229], 0
	v_mfma_f32_16x16x32_bf16 v[28:31], v[182:185], v[234:237], v[28:31]
	v_mfma_f32_16x16x32_bf16 v[16:19], v[168:171], v[230:233], 0
	v_mfma_f32_16x16x32_bf16 v[16:19], v[174:177], v[238:241], v[16:19]
	v_mfma_f32_16x16x32_bf16 v[12:15], v[178:181], v[230:233], 0
	v_mfma_f32_16x16x32_bf16 v[12:15], v[182:185], v[238:241], v[12:15]
	v_mfma_f32_16x16x32_bf16 v[56:59], v[194:197], v[210:213], 0
	v_mfma_f32_16x16x32_bf16 v[56:59], v[198:201], v[218:221], v[56:59]
	v_mfma_f32_16x16x32_bf16 v[52:55], v[202:205], v[210:213], 0
	v_mfma_f32_16x16x32_bf16 v[52:55], v[206:209], v[218:221], v[52:55]
	v_mfma_f32_16x16x32_bf16 v[40:43], v[194:197], v[214:217], 0
	v_mfma_f32_16x16x32_bf16 v[40:43], v[198:201], v[222:225], v[40:43]
	v_mfma_f32_16x16x32_bf16 v[36:39], v[202:205], v[214:217], 0
	v_mfma_f32_16x16x32_bf16 v[36:39], v[206:209], v[222:225], v[36:39]
	v_mfma_f32_16x16x32_bf16 v[24:27], v[194:197], v[226:229], 0
	v_mfma_f32_16x16x32_bf16 v[24:27], v[198:201], v[234:237], v[24:27]
	v_mfma_f32_16x16x32_bf16 v[20:23], v[202:205], v[226:229], 0
	v_mfma_f32_16x16x32_bf16 v[20:23], v[206:209], v[234:237], v[20:23]
	v_mfma_f32_16x16x32_bf16 v[8:11], v[194:197], v[230:233], 0
	v_mfma_f32_16x16x32_bf16 v[8:11], v[198:201], v[238:241], v[8:11]
	v_mfma_f32_16x16x32_bf16 v[4:7], v[202:205], v[230:233], 0
	v_mfma_f32_16x16x32_bf16 v[4:7], v[206:209], v[238:241], v[4:7]
	s_barrier
	ds_read_b128 v[168:171], v163
	ds_read_b128 v[174:177], v164
	ds_read_b128 v[178:181], v155
	ds_read_b128 v[182:185], v160
	ds_read_b128 v[194:197], v165
	ds_read_b128 v[198:201], v166
	ds_read_b128 v[202:205], v161
	ds_read_b128 v[206:209], v162
	s_mov_b32 m0, s34
	v_lshl_add_u64 v[242:243], s[70:71], 0, v[0:1]
	ds_read_b128 v[210:213], v153 offset:32768
	ds_read_b128 v[214:217], v153 offset:34816
	ds_read_b128 v[218:221], v154 offset:32768
	ds_read_b128 v[222:225], v154 offset:34816
	ds_read_b128 v[226:229], v153 offset:36864
	ds_read_b128 v[230:233], v153 offset:38912
	ds_read_b128 v[234:237], v154 offset:36864
	ds_read_b128 v[238:241], v154 offset:38912
	global_load_lds_dwordx4 v[242:243], off
	v_lshl_add_u64 v[244:245], v[242:243], 0, s[16:17]
	s_mov_b32 m0, s35
	s_nop 0
	global_load_lds_dwordx4 v[244:245], off
	v_lshl_add_u64 v[244:245], v[242:243], 0, s[0:1]
	s_mov_b32 m0, s38
	v_lshl_add_u64 v[242:243], v[242:243], 0, s[18:19]
	global_load_lds_dwordx4 v[244:245], off
	s_mov_b32 m0, s39
	s_nop 0
	global_load_lds_dwordx4 v[242:243], off
	s_waitcnt vmcnt(8)
	s_waitcnt lgkmcnt(0)
	s_barrier
	v_mfma_f32_16x16x32_bf16 v[128:131], v[168:171], v[210:213], v[128:131]
	v_mfma_f32_16x16x32_bf16 v[128:131], v[174:177], v[218:221], v[128:131]
	v_mfma_f32_16x16x32_bf16 v[124:127], v[178:181], v[210:213], v[124:127]
	v_mfma_f32_16x16x32_bf16 v[124:127], v[182:185], v[218:221], v[124:127]
	v_mfma_f32_16x16x32_bf16 v[112:115], v[168:171], v[214:217], v[112:115]
	v_mfma_f32_16x16x32_bf16 v[112:115], v[174:177], v[222:225], v[112:115]
	v_mfma_f32_16x16x32_bf16 v[108:111], v[178:181], v[214:217], v[108:111]
	v_mfma_f32_16x16x32_bf16 v[108:111], v[182:185], v[222:225], v[108:111]
	v_mfma_f32_16x16x32_bf16 v[96:99], v[168:171], v[226:229], v[96:99]
	v_mfma_f32_16x16x32_bf16 v[96:99], v[174:177], v[234:237], v[96:99]
	v_mfma_f32_16x16x32_bf16 v[92:95], v[178:181], v[226:229], v[92:95]
	v_mfma_f32_16x16x32_bf16 v[92:95], v[182:185], v[234:237], v[92:95]
	v_mfma_f32_16x16x32_bf16 v[80:83], v[168:171], v[230:233], v[80:83]
	v_mfma_f32_16x16x32_bf16 v[80:83], v[174:177], v[238:241], v[80:83]
	v_mfma_f32_16x16x32_bf16 v[76:79], v[178:181], v[230:233], v[76:79]
	v_mfma_f32_16x16x32_bf16 v[76:79], v[182:185], v[238:241], v[76:79]
	v_mfma_f32_16x16x32_bf16 v[120:123], v[194:197], v[210:213], v[120:123]
	v_mfma_f32_16x16x32_bf16 v[120:123], v[198:201], v[218:221], v[120:123]
	v_mfma_f32_16x16x32_bf16 v[116:119], v[202:205], v[210:213], v[116:119]
	v_mfma_f32_16x16x32_bf16 v[116:119], v[206:209], v[218:221], v[116:119]
	v_mfma_f32_16x16x32_bf16 v[104:107], v[194:197], v[214:217], v[104:107]
	v_mfma_f32_16x16x32_bf16 v[104:107], v[198:201], v[222:225], v[104:107]
	v_mfma_f32_16x16x32_bf16 v[100:103], v[202:205], v[214:217], v[100:103]
	v_mfma_f32_16x16x32_bf16 v[100:103], v[206:209], v[222:225], v[100:103]
	v_mfma_f32_16x16x32_bf16 v[88:91], v[194:197], v[226:229], v[88:91]
	v_mfma_f32_16x16x32_bf16 v[88:91], v[198:201], v[234:237], v[88:91]
	v_mfma_f32_16x16x32_bf16 v[84:87], v[202:205], v[226:229], v[84:87]
	v_mfma_f32_16x16x32_bf16 v[84:87], v[206:209], v[234:237], v[84:87]
	v_mfma_f32_16x16x32_bf16 v[72:75], v[194:197], v[230:233], v[72:75]
	v_mfma_f32_16x16x32_bf16 v[72:75], v[198:201], v[238:241], v[72:75]
	v_mfma_f32_16x16x32_bf16 v[68:71], v[202:205], v[230:233], v[68:71]
	v_mfma_f32_16x16x32_bf16 v[68:71], v[206:209], v[238:241], v[68:71]
	s_barrier
	s_add_i32 s70, s73, s3
	v_lshl_add_u64 v[242:243], v[140:141], 0, s[22:23]
	s_mov_b32 m0, s70
	ds_read_b128 v[210:213], v153 offset:49152
	ds_read_b128 v[214:217], v153 offset:51200
	ds_read_b128 v[218:221], v154 offset:49152
	ds_read_b128 v[222:225], v154 offset:51200
	ds_read_b128 v[226:229], v153 offset:53248
	ds_read_b128 v[230:233], v153 offset:55296
	ds_read_b128 v[234:237], v154 offset:53248
	ds_read_b128 v[238:241], v154 offset:55296
	global_load_lds_dwordx4 v[242:243], off
	v_lshl_add_u64 v[242:243], v[140:141], 0, s[24:25]
	s_add_i32 m0, s70, 0x2000
	s_add_i32 s70, s77, s3
	global_load_lds_dwordx4 v[242:243], off
	v_lshl_add_u64 v[242:243], v[140:141], 0, s[28:29]
	s_mov_b32 m0, s70
	v_lshl_add_u64 v[140:141], v[140:141], 0, s[36:37]
	global_load_lds_dwordx4 v[242:243], off
	s_add_i32 m0, s70, 0x2000
	s_nop 0
	global_load_lds_dwordx4 v[140:141], off
	s_waitcnt vmcnt(4)
	s_waitcnt lgkmcnt(0)
	s_barrier
	v_mfma_f32_16x16x32_bf16 v[64:67], v[168:171], v[210:213], v[64:67]
	v_mfma_f32_16x16x32_bf16 v[64:67], v[174:177], v[218:221], v[64:67]
	v_mfma_f32_16x16x32_bf16 v[60:63], v[178:181], v[210:213], v[60:63]
	v_mfma_f32_16x16x32_bf16 v[60:63], v[182:185], v[218:221], v[60:63]
	v_mfma_f32_16x16x32_bf16 v[48:51], v[168:171], v[214:217], v[48:51]
	v_mfma_f32_16x16x32_bf16 v[48:51], v[174:177], v[222:225], v[48:51]
	v_mfma_f32_16x16x32_bf16 v[44:47], v[178:181], v[214:217], v[44:47]
	v_mfma_f32_16x16x32_bf16 v[44:47], v[182:185], v[222:225], v[44:47]
	v_mfma_f32_16x16x32_bf16 v[32:35], v[168:171], v[226:229], v[32:35]
	v_mfma_f32_16x16x32_bf16 v[32:35], v[174:177], v[234:237], v[32:35]
	v_mfma_f32_16x16x32_bf16 v[28:31], v[178:181], v[226:229], v[28:31]
	v_mfma_f32_16x16x32_bf16 v[28:31], v[182:185], v[234:237], v[28:31]
	v_mfma_f32_16x16x32_bf16 v[16:19], v[168:171], v[230:233], v[16:19]
	v_mfma_f32_16x16x32_bf16 v[16:19], v[174:177], v[238:241], v[16:19]
	v_mfma_f32_16x16x32_bf16 v[12:15], v[178:181], v[230:233], v[12:15]
	v_mfma_f32_16x16x32_bf16 v[12:15], v[182:185], v[238:241], v[12:15]
	v_mfma_f32_16x16x32_bf16 v[56:59], v[194:197], v[210:213], v[56:59]
	v_mfma_f32_16x16x32_bf16 v[56:59], v[198:201], v[218:221], v[56:59]
	v_mfma_f32_16x16x32_bf16 v[52:55], v[202:205], v[210:213], v[52:55]
	v_mfma_f32_16x16x32_bf16 v[52:55], v[206:209], v[218:221], v[52:55]
	v_mfma_f32_16x16x32_bf16 v[40:43], v[194:197], v[214:217], v[40:43]
	v_mfma_f32_16x16x32_bf16 v[40:43], v[198:201], v[222:225], v[40:43]
	v_mfma_f32_16x16x32_bf16 v[36:39], v[202:205], v[214:217], v[36:39]
	v_mfma_f32_16x16x32_bf16 v[36:39], v[206:209], v[222:225], v[36:39]
	v_mfma_f32_16x16x32_bf16 v[24:27], v[194:197], v[226:229], v[24:27]
	v_mfma_f32_16x16x32_bf16 v[24:27], v[198:201], v[234:237], v[24:27]
	v_mfma_f32_16x16x32_bf16 v[20:23], v[202:205], v[226:229], v[20:23]
	v_mfma_f32_16x16x32_bf16 v[20:23], v[206:209], v[234:237], v[20:23]
	v_mfma_f32_16x16x32_bf16 v[8:11], v[194:197], v[230:233], v[8:11]
	v_mfma_f32_16x16x32_bf16 v[8:11], v[198:201], v[238:241], v[8:11]
	v_mfma_f32_16x16x32_bf16 v[4:7], v[202:205], v[230:233], v[4:7]
	v_mfma_f32_16x16x32_bf16 v[4:7], v[206:209], v[238:241], v[4:7]
	s_barrier
	s_add_i32 s83, s83, 2
	s_add_u32 s68, s68, 0x100
	s_addc_u32 s69, s69, 0
	s_cmp_gt_u32 s83, 13
.LBB0_1135:
	ds_read_b128 v[168:171], v145
	ds_read_b128 v[174:177], v146
	ds_read_b128 v[178:181], v147
	ds_read_b128 v[182:185], v148
	ds_read_b128 v[194:197], v149
	ds_read_b128 v[198:201], v150
	ds_read_b128 v[202:205], v151
	ds_read_b128 v[206:209], v152
	s_add_u32 s70, s26, s68
	s_addc_u32 s71, s27, s69
	s_add_u32 s70, s70, 0x100
	s_addc_u32 s71, s71, 0
	s_add_u32 s84, s81, s68
	s_addc_u32 s85, s82, s69
	s_cmpk_eq_i32 s68, 0x700
	s_cselect_b32 s85, s59, s85
	s_cselect_b32 s84, s80, s84
	s_cselect_b32 s71, s57, s71
	s_cselect_b32 s70, s79, s70
	v_lshl_add_u64 v[140:141], v[138:139], 0, s[68:69]
	v_lshl_add_u64 v[242:243], v[140:141], 0, s[22:23]
	s_add_i32 m0, s34, 0x8000
	s_mov_b64 s[86:87], 0x20080
	ds_read_b128 v[210:213], v153
	ds_read_b128 v[214:217], v153 offset:2048
	ds_read_b128 v[218:221], v154
	ds_read_b128 v[222:225], v154 offset:2048
	ds_read_b128 v[226:229], v153 offset:4096
	ds_read_b128 v[230:233], v153 offset:6144
	ds_read_b128 v[234:237], v154 offset:4096
	ds_read_b128 v[238:241], v154 offset:6144
	global_load_lds_dwordx4 v[242:243], off
	v_lshl_add_u64 v[242:243], v[140:141], 0, s[86:87]
	s_add_i32 m0, s34, 0xa000
	s_mov_b64 s[86:87], 0x60080
	global_load_lds_dwordx4 v[242:243], off
	v_lshl_add_u64 v[242:243], v[140:141], 0, s[24:25]
	s_add_i32 m0, s34, 0xc000
	v_lshl_add_u64 v[140:141], v[140:141], 0, s[86:87]
	global_load_lds_dwordx4 v[242:243], off
	s_add_i32 m0, s34, 0xe000
	s_nop 0
	global_load_lds_dwordx4 v[140:141], off
	s_waitcnt vmcnt(8)
	s_waitcnt lgkmcnt(0)
	s_barrier
	v_mfma_f32_16x16x32_bf16 v[128:131], v[168:171], v[210:213], v[128:131]
	v_mfma_f32_16x16x32_bf16 v[128:131], v[174:177], v[218:221], v[128:131]
	v_mfma_f32_16x16x32_bf16 v[124:127], v[178:181], v[210:213], v[124:127]
	v_mfma_f32_16x16x32_bf16 v[124:127], v[182:185], v[218:221], v[124:127]
	v_mfma_f32_16x16x32_bf16 v[112:115], v[168:171], v[214:217], v[112:115]
	v_mfma_f32_16x16x32_bf16 v[112:115], v[174:177], v[222:225], v[112:115]
	v_mfma_f32_16x16x32_bf16 v[108:111], v[178:181], v[214:217], v[108:111]
	v_mfma_f32_16x16x32_bf16 v[108:111], v[182:185], v[222:225], v[108:111]
	v_mfma_f32_16x16x32_bf16 v[96:99], v[168:171], v[226:229], v[96:99]
	v_mfma_f32_16x16x32_bf16 v[96:99], v[174:177], v[234:237], v[96:99]
	v_mfma_f32_16x16x32_bf16 v[92:95], v[178:181], v[226:229], v[92:95]
	v_mfma_f32_16x16x32_bf16 v[92:95], v[182:185], v[234:237], v[92:95]
	v_mfma_f32_16x16x32_bf16 v[80:83], v[168:171], v[230:233], v[80:83]
	v_mfma_f32_16x16x32_bf16 v[80:83], v[174:177], v[238:241], v[80:83]
	v_mfma_f32_16x16x32_bf16 v[76:79], v[178:181], v[230:233], v[76:79]
	v_mfma_f32_16x16x32_bf16 v[76:79], v[182:185], v[238:241], v[76:79]
	v_mfma_f32_16x16x32_bf16 v[120:123], v[194:197], v[210:213], v[120:123]
	v_mfma_f32_16x16x32_bf16 v[120:123], v[198:201], v[218:221], v[120:123]
	v_mfma_f32_16x16x32_bf16 v[116:119], v[202:205], v[210:213], v[116:119]
	v_mfma_f32_16x16x32_bf16 v[116:119], v[206:209], v[218:221], v[116:119]
	v_mfma_f32_16x16x32_bf16 v[104:107], v[194:197], v[214:217], v[104:107]
	v_mfma_f32_16x16x32_bf16 v[104:107], v[198:201], v[222:225], v[104:107]
	v_mfma_f32_16x16x32_bf16 v[100:103], v[202:205], v[214:217], v[100:103]
	v_mfma_f32_16x16x32_bf16 v[100:103], v[206:209], v[222:225], v[100:103]
	v_mfma_f32_16x16x32_bf16 v[88:91], v[194:197], v[226:229], v[88:91]
	v_mfma_f32_16x16x32_bf16 v[88:91], v[198:201], v[234:237], v[88:91]
	v_mfma_f32_16x16x32_bf16 v[84:87], v[202:205], v[226:229], v[84:87]
	v_mfma_f32_16x16x32_bf16 v[84:87], v[206:209], v[234:237], v[84:87]
	v_mfma_f32_16x16x32_bf16 v[72:75], v[194:197], v[230:233], v[72:75]
	v_mfma_f32_16x16x32_bf16 v[72:75], v[198:201], v[238:241], v[72:75]
	v_mfma_f32_16x16x32_bf16 v[68:71], v[202:205], v[230:233], v[68:71]
	v_mfma_f32_16x16x32_bf16 v[68:71], v[206:209], v[238:241], v[68:71]
	s_barrier
	v_lshl_add_u64 v[140:141], s[84:85], 0, v[158:159]
	s_add_i32 s84, s67, s3
	s_mov_b32 m0, s84
	ds_read_b128 v[210:213], v153 offset:16384
	ds_read_b128 v[214:217], v153 offset:18432
	ds_read_b128 v[218:221], v154 offset:16384
	ds_read_b128 v[222:225], v154 offset:18432
	ds_read_b128 v[226:229], v153 offset:20480
	ds_read_b128 v[230:233], v153 offset:22528
	ds_read_b128 v[234:237], v154 offset:20480
	ds_read_b128 v[238:241], v154 offset:22528
	global_load_lds_dwordx4 v[140:141], off
	v_lshl_add_u64 v[242:243], v[140:141], 0, s[0:1]
	s_add_i32 m0, s84, 0x2000
	s_add_i32 s84, s72, s3
	global_load_lds_dwordx4 v[242:243], off
	v_lshl_add_u64 v[242:243], v[140:141], 0, s[12:13]
	s_mov_b32 m0, s84
	s_nop 0
	global_load_lds_dwordx4 v[242:243], off
	v_lshl_add_u64 v[242:243], v[140:141], 0, s[14:15]
	s_add_i32 m0, s84, 0x2000
	s_nop 0
	global_load_lds_dwordx4 v[242:243], off
	s_waitcnt vmcnt(4)
	s_waitcnt lgkmcnt(0)
	s_barrier
	v_mfma_f32_16x16x32_bf16 v[64:67], v[168:171], v[210:213], v[64:67]
	v_mfma_f32_16x16x32_bf16 v[64:67], v[174:177], v[218:221], v[64:67]
	v_mfma_f32_16x16x32_bf16 v[60:63], v[178:181], v[210:213], v[60:63]
	v_mfma_f32_16x16x32_bf16 v[60:63], v[182:185], v[218:221], v[60:63]
	v_mfma_f32_16x16x32_bf16 v[48:51], v[168:171], v[214:217], v[48:51]
	v_mfma_f32_16x16x32_bf16 v[48:51], v[174:177], v[222:225], v[48:51]
	v_mfma_f32_16x16x32_bf16 v[44:47], v[178:181], v[214:217], v[44:47]
	v_mfma_f32_16x16x32_bf16 v[44:47], v[182:185], v[222:225], v[44:47]
	v_mfma_f32_16x16x32_bf16 v[32:35], v[168:171], v[226:229], v[32:35]
	v_mfma_f32_16x16x32_bf16 v[32:35], v[174:177], v[234:237], v[32:35]
	v_mfma_f32_16x16x32_bf16 v[28:31], v[178:181], v[226:229], v[28:31]
	v_mfma_f32_16x16x32_bf16 v[28:31], v[182:185], v[234:237], v[28:31]
	v_mfma_f32_16x16x32_bf16 v[16:19], v[168:171], v[230:233], v[16:19]
	v_mfma_f32_16x16x32_bf16 v[16:19], v[174:177], v[238:241], v[16:19]
	v_mfma_f32_16x16x32_bf16 v[12:15], v[178:181], v[230:233], v[12:15]
	v_mfma_f32_16x16x32_bf16 v[12:15], v[182:185], v[238:241], v[12:15]
	v_mfma_f32_16x16x32_bf16 v[56:59], v[194:197], v[210:213], v[56:59]
	v_mfma_f32_16x16x32_bf16 v[56:59], v[198:201], v[218:221], v[56:59]
	v_mfma_f32_16x16x32_bf16 v[52:55], v[202:205], v[210:213], v[52:55]
	v_mfma_f32_16x16x32_bf16 v[52:55], v[206:209], v[218:221], v[52:55]
	v_mfma_f32_16x16x32_bf16 v[40:43], v[194:197], v[214:217], v[40:43]
	v_mfma_f32_16x16x32_bf16 v[40:43], v[198:201], v[222:225], v[40:43]
	v_mfma_f32_16x16x32_bf16 v[36:39], v[202:205], v[214:217], v[36:39]
	v_mfma_f32_16x16x32_bf16 v[36:39], v[206:209], v[222:225], v[36:39]
	v_mfma_f32_16x16x32_bf16 v[24:27], v[194:197], v[226:229], v[24:27]
	v_mfma_f32_16x16x32_bf16 v[24:27], v[198:201], v[234:237], v[24:27]
	v_mfma_f32_16x16x32_bf16 v[20:23], v[202:205], v[226:229], v[20:23]
	v_mfma_f32_16x16x32_bf16 v[20:23], v[206:209], v[234:237], v[20:23]
	v_mfma_f32_16x16x32_bf16 v[8:11], v[194:197], v[230:233], v[8:11]
	v_mfma_f32_16x16x32_bf16 v[8:11], v[198:201], v[238:241], v[8:11]
	v_mfma_f32_16x16x32_bf16 v[4:7], v[202:205], v[230:233], v[4:7]
	v_mfma_f32_16x16x32_bf16 v[4:7], v[206:209], v[238:241], v[4:7]
	s_barrier
	ds_read_b128 v[168:171], v163
	ds_read_b128 v[174:177], v164
	ds_read_b128 v[178:181], v155
	ds_read_b128 v[182:185], v160
	ds_read_b128 v[194:197], v165
	ds_read_b128 v[198:201], v166
	ds_read_b128 v[202:205], v161
	ds_read_b128 v[206:209], v162
	s_mov_b32 m0, s34
	v_lshl_add_u64 v[242:243], s[70:71], 0, v[0:1]
	ds_read_b128 v[210:213], v153 offset:32768
	ds_read_b128 v[214:217], v153 offset:34816
	ds_read_b128 v[218:221], v154 offset:32768
	ds_read_b128 v[222:225], v154 offset:34816
	ds_read_b128 v[226:229], v153 offset:36864
	ds_read_b128 v[230:233], v153 offset:38912
	ds_read_b128 v[234:237], v154 offset:36864
	ds_read_b128 v[238:241], v154 offset:38912
	global_load_lds_dwordx4 v[242:243], off
	v_lshl_add_u64 v[244:245], v[242:243], 0, s[16:17]
	s_mov_b32 m0, s35
	s_nop 0
	global_load_lds_dwordx4 v[244:245], off
	v_lshl_add_u64 v[244:245], v[242:243], 0, s[0:1]
	s_mov_b32 m0, s38
	v_lshl_add_u64 v[242:243], v[242:243], 0, s[18:19]
	global_load_lds_dwordx4 v[244:245], off
	s_mov_b32 m0, s39
	s_nop 0
	global_load_lds_dwordx4 v[242:243], off
	s_waitcnt vmcnt(8)
	s_waitcnt lgkmcnt(0)
	s_barrier
	v_mfma_f32_16x16x32_bf16 v[128:131], v[168:171], v[210:213], v[128:131]
	v_mfma_f32_16x16x32_bf16 v[128:131], v[174:177], v[218:221], v[128:131]
	v_mfma_f32_16x16x32_bf16 v[124:127], v[178:181], v[210:213], v[124:127]
	v_mfma_f32_16x16x32_bf16 v[124:127], v[182:185], v[218:221], v[124:127]
	v_mfma_f32_16x16x32_bf16 v[112:115], v[168:171], v[214:217], v[112:115]
	v_mfma_f32_16x16x32_bf16 v[112:115], v[174:177], v[222:225], v[112:115]
	v_mfma_f32_16x16x32_bf16 v[108:111], v[178:181], v[214:217], v[108:111]
	v_mfma_f32_16x16x32_bf16 v[108:111], v[182:185], v[222:225], v[108:111]
	v_mfma_f32_16x16x32_bf16 v[96:99], v[168:171], v[226:229], v[96:99]
	v_mfma_f32_16x16x32_bf16 v[96:99], v[174:177], v[234:237], v[96:99]
	v_mfma_f32_16x16x32_bf16 v[92:95], v[178:181], v[226:229], v[92:95]
	v_mfma_f32_16x16x32_bf16 v[92:95], v[182:185], v[234:237], v[92:95]
	v_mfma_f32_16x16x32_bf16 v[80:83], v[168:171], v[230:233], v[80:83]
	v_mfma_f32_16x16x32_bf16 v[80:83], v[174:177], v[238:241], v[80:83]
	v_mfma_f32_16x16x32_bf16 v[76:79], v[178:181], v[230:233], v[76:79]
	v_mfma_f32_16x16x32_bf16 v[76:79], v[182:185], v[238:241], v[76:79]
	v_mfma_f32_16x16x32_bf16 v[120:123], v[194:197], v[210:213], v[120:123]
	v_mfma_f32_16x16x32_bf16 v[120:123], v[198:201], v[218:221], v[120:123]
	v_mfma_f32_16x16x32_bf16 v[116:119], v[202:205], v[210:213], v[116:119]
	v_mfma_f32_16x16x32_bf16 v[116:119], v[206:209], v[218:221], v[116:119]
	v_mfma_f32_16x16x32_bf16 v[104:107], v[194:197], v[214:217], v[104:107]
	v_mfma_f32_16x16x32_bf16 v[104:107], v[198:201], v[222:225], v[104:107]
	v_mfma_f32_16x16x32_bf16 v[100:103], v[202:205], v[214:217], v[100:103]
	v_mfma_f32_16x16x32_bf16 v[100:103], v[206:209], v[222:225], v[100:103]
	v_mfma_f32_16x16x32_bf16 v[88:91], v[194:197], v[226:229], v[88:91]
	v_mfma_f32_16x16x32_bf16 v[88:91], v[198:201], v[234:237], v[88:91]
	v_mfma_f32_16x16x32_bf16 v[84:87], v[202:205], v[226:229], v[84:87]
	v_mfma_f32_16x16x32_bf16 v[84:87], v[206:209], v[234:237], v[84:87]
	v_mfma_f32_16x16x32_bf16 v[72:75], v[194:197], v[230:233], v[72:75]
	v_mfma_f32_16x16x32_bf16 v[72:75], v[198:201], v[238:241], v[72:75]
	v_mfma_f32_16x16x32_bf16 v[68:71], v[202:205], v[230:233], v[68:71]
	v_mfma_f32_16x16x32_bf16 v[68:71], v[206:209], v[238:241], v[68:71]
	s_barrier
	s_add_i32 s70, s73, s3
	v_lshl_add_u64 v[242:243], v[140:141], 0, s[22:23]
	s_mov_b32 m0, s70
	ds_read_b128 v[210:213], v153 offset:49152
	ds_read_b128 v[214:217], v153 offset:51200
	ds_read_b128 v[218:221], v154 offset:49152
	ds_read_b128 v[222:225], v154 offset:51200
	ds_read_b128 v[226:229], v153 offset:53248
	ds_read_b128 v[230:233], v153 offset:55296
	ds_read_b128 v[234:237], v154 offset:53248
	ds_read_b128 v[238:241], v154 offset:55296
	global_load_lds_dwordx4 v[242:243], off
	v_lshl_add_u64 v[242:243], v[140:141], 0, s[24:25]
	s_add_i32 m0, s70, 0x2000
	s_add_i32 s70, s77, s3
	global_load_lds_dwordx4 v[242:243], off
	v_lshl_add_u64 v[242:243], v[140:141], 0, s[28:29]
	s_mov_b32 m0, s70
	v_lshl_add_u64 v[140:141], v[140:141], 0, s[36:37]
	global_load_lds_dwordx4 v[242:243], off
	s_add_i32 m0, s70, 0x2000
	s_nop 0
	global_load_lds_dwordx4 v[140:141], off
	s_waitcnt vmcnt(4)
	s_waitcnt lgkmcnt(0)
	s_barrier
	v_mfma_f32_16x16x32_bf16 v[64:67], v[168:171], v[210:213], v[64:67]
	v_mfma_f32_16x16x32_bf16 v[64:67], v[174:177], v[218:221], v[64:67]
	v_mfma_f32_16x16x32_bf16 v[60:63], v[178:181], v[210:213], v[60:63]
	v_mfma_f32_16x16x32_bf16 v[60:63], v[182:185], v[218:221], v[60:63]
	v_mfma_f32_16x16x32_bf16 v[48:51], v[168:171], v[214:217], v[48:51]
	v_mfma_f32_16x16x32_bf16 v[48:51], v[174:177], v[222:225], v[48:51]
	v_mfma_f32_16x16x32_bf16 v[44:47], v[178:181], v[214:217], v[44:47]
	v_mfma_f32_16x16x32_bf16 v[44:47], v[182:185], v[222:225], v[44:47]
	v_mfma_f32_16x16x32_bf16 v[32:35], v[168:171], v[226:229], v[32:35]
	v_mfma_f32_16x16x32_bf16 v[32:35], v[174:177], v[234:237], v[32:35]
	v_mfma_f32_16x16x32_bf16 v[28:31], v[178:181], v[226:229], v[28:31]
	v_mfma_f32_16x16x32_bf16 v[28:31], v[182:185], v[234:237], v[28:31]
	v_mfma_f32_16x16x32_bf16 v[16:19], v[168:171], v[230:233], v[16:19]
	v_mfma_f32_16x16x32_bf16 v[16:19], v[174:177], v[238:241], v[16:19]
	v_mfma_f32_16x16x32_bf16 v[12:15], v[178:181], v[230:233], v[12:15]
	v_mfma_f32_16x16x32_bf16 v[12:15], v[182:185], v[238:241], v[12:15]
	v_mfma_f32_16x16x32_bf16 v[56:59], v[194:197], v[210:213], v[56:59]
	v_mfma_f32_16x16x32_bf16 v[56:59], v[198:201], v[218:221], v[56:59]
	v_mfma_f32_16x16x32_bf16 v[52:55], v[202:205], v[210:213], v[52:55]
	v_mfma_f32_16x16x32_bf16 v[52:55], v[206:209], v[218:221], v[52:55]
	v_mfma_f32_16x16x32_bf16 v[40:43], v[194:197], v[214:217], v[40:43]
	v_mfma_f32_16x16x32_bf16 v[40:43], v[198:201], v[222:225], v[40:43]
	v_mfma_f32_16x16x32_bf16 v[36:39], v[202:205], v[214:217], v[36:39]
	v_mfma_f32_16x16x32_bf16 v[36:39], v[206:209], v[222:225], v[36:39]
	v_mfma_f32_16x16x32_bf16 v[24:27], v[194:197], v[226:229], v[24:27]
	v_mfma_f32_16x16x32_bf16 v[24:27], v[198:201], v[234:237], v[24:27]
	v_mfma_f32_16x16x32_bf16 v[20:23], v[202:205], v[226:229], v[20:23]
	v_mfma_f32_16x16x32_bf16 v[20:23], v[206:209], v[234:237], v[20:23]
	v_mfma_f32_16x16x32_bf16 v[8:11], v[194:197], v[230:233], v[8:11]
	v_mfma_f32_16x16x32_bf16 v[8:11], v[198:201], v[238:241], v[8:11]
	v_mfma_f32_16x16x32_bf16 v[4:7], v[202:205], v[230:233], v[4:7]
	v_mfma_f32_16x16x32_bf16 v[4:7], v[206:209], v[238:241], v[4:7]
	s_barrier
	s_add_i32 s83, s83, 2
	s_add_u32 s68, s68, 0x100
	s_addc_u32 s69, s69, 0
	s_cmp_gt_u32 s83, 13
	s_cbranch_scc0 .LBB0_1135
	s_and_b64 vcc, exec, s[40:41]
	s_cbranch_vccz .LBB0_1138
	s_barrier

.LBB0_1371:
	v_add_u32_e32 v147, s64, v143
	v_add_u32_e32 v152, s64, v144
	ds_read_b128 v[148:151], v147
	ds_read_b128 v[152:155], v152
	v_add_u32_e32 v147, s65, v143
	v_add_u32_e32 v162, s65, v144
	s_add_u32 s58, s18, s56
	ds_read_b128 v[158:161], v147
	ds_read_b128 v[162:165], v162
	v_add_u32_e32 v147, s66, v143
	s_addc_u32 s59, s19, s57
	v_add_u32_e32 v166, s66, v144
	ds_read_b128 v[170:173], v147
	ds_read_b128 v[174:177], v166
	v_add_u32_e32 v147, s67, v143
	s_add_u32 s58, s58, 0x100
	v_add_u32_e32 v166, s67, v144
	ds_read_b128 v[178:181], v147
	ds_read_b128 v[182:185], v166
	s_addc_u32 s59, s59, 0
	s_add_u32 s78, s53, s56
	s_addc_u32 s79, s72, s57
	s_cmpk_eq_i32 s56, 0x1f00
	s_cselect_b32 s79, s49, s79
	s_cselect_b32 s78, s76, s78
	s_cselect_b32 s59, s51, s59
	s_cselect_b32 s58, s73, s58
	v_lshl_add_u64 v[166:167], v[140:141], 0, s[56:57]
	v_lshl_add_u64 v[218:219], v[166:167], 0, s[24:25]
	s_add_i32 m0, s35, 0x8000
	ds_read_b128 v[186:189], v145
	ds_read_b128 v[190:193], v145 offset:2048
	ds_read_b128 v[194:197], v146
	ds_read_b128 v[198:201], v146 offset:2048
	ds_read_b128 v[202:205], v145 offset:4096
	ds_read_b128 v[206:209], v145 offset:6144
	ds_read_b128 v[210:213], v146 offset:4096
	ds_read_b128 v[214:217], v146 offset:6144
	global_load_lds_dwordx4 v[218:219], off
	v_lshl_add_u64 v[218:219], v[166:167], 0, s[44:45]
	s_add_i32 m0, s35, 0xa000
	s_nop 0
	global_load_lds_dwordx4 v[218:219], off
	v_lshl_add_u64 v[218:219], v[166:167], 0, s[28:29]
	s_add_i32 m0, s35, 0xc000
	v_lshl_add_u64 v[166:167], v[166:167], 0, s[46:47]
	global_load_lds_dwordx4 v[218:219], off
	s_add_i32 m0, s35, 0xe000
	s_nop 0
	global_load_lds_dwordx4 v[166:167], off
	s_waitcnt vmcnt(8)
	s_waitcnt lgkmcnt(0)
	s_barrier
	v_mfma_f32_16x16x32_bf16 v[128:131], v[148:151], v[186:189], v[128:131]
	v_mfma_f32_16x16x32_bf16 v[128:131], v[152:155], v[194:197], v[128:131]
	v_mfma_f32_16x16x32_bf16 v[124:127], v[158:161], v[186:189], v[124:127]
	v_mfma_f32_16x16x32_bf16 v[124:127], v[162:165], v[194:197], v[124:127]
	v_mfma_f32_16x16x32_bf16 v[112:115], v[148:151], v[190:193], v[112:115]
	v_mfma_f32_16x16x32_bf16 v[112:115], v[152:155], v[198:201], v[112:115]
	v_mfma_f32_16x16x32_bf16 v[108:111], v[158:161], v[190:193], v[108:111]
	v_mfma_f32_16x16x32_bf16 v[108:111], v[162:165], v[198:201], v[108:111]
	v_mfma_f32_16x16x32_bf16 v[96:99], v[148:151], v[202:205], v[96:99]
	v_mfma_f32_16x16x32_bf16 v[96:99], v[152:155], v[210:213], v[96:99]
	v_mfma_f32_16x16x32_bf16 v[92:95], v[158:161], v[202:205], v[92:95]
	v_mfma_f32_16x16x32_bf16 v[92:95], v[162:165], v[210:213], v[92:95]
	v_mfma_f32_16x16x32_bf16 v[80:83], v[148:151], v[206:209], v[80:83]
	v_mfma_f32_16x16x32_bf16 v[80:83], v[152:155], v[214:217], v[80:83]
	v_mfma_f32_16x16x32_bf16 v[76:79], v[158:161], v[206:209], v[76:79]
	v_mfma_f32_16x16x32_bf16 v[76:79], v[162:165], v[214:217], v[76:79]
	v_mfma_f32_16x16x32_bf16 v[120:123], v[170:173], v[186:189], v[120:123]
	v_mfma_f32_16x16x32_bf16 v[120:123], v[174:177], v[194:197], v[120:123]
	v_mfma_f32_16x16x32_bf16 v[116:119], v[178:181], v[186:189], v[116:119]
	v_mfma_f32_16x16x32_bf16 v[116:119], v[182:185], v[194:197], v[116:119]
	v_mfma_f32_16x16x32_bf16 v[104:107], v[170:173], v[190:193], v[104:107]
	v_mfma_f32_16x16x32_bf16 v[104:107], v[174:177], v[198:201], v[104:107]
	v_mfma_f32_16x16x32_bf16 v[100:103], v[178:181], v[190:193], v[100:103]
	v_mfma_f32_16x16x32_bf16 v[100:103], v[182:185], v[198:201], v[100:103]
	v_mfma_f32_16x16x32_bf16 v[88:91], v[170:173], v[202:205], v[88:91]
	v_mfma_f32_16x16x32_bf16 v[88:91], v[174:177], v[210:213], v[88:91]
	v_mfma_f32_16x16x32_bf16 v[84:87], v[178:181], v[202:205], v[84:87]
	v_mfma_f32_16x16x32_bf16 v[84:87], v[182:185], v[210:213], v[84:87]
	v_mfma_f32_16x16x32_bf16 v[72:75], v[170:173], v[206:209], v[72:75]
	v_mfma_f32_16x16x32_bf16 v[72:75], v[174:177], v[214:217], v[72:75]
	v_mfma_f32_16x16x32_bf16 v[68:71], v[178:181], v[206:209], v[68:71]
	v_mfma_f32_16x16x32_bf16 v[68:71], v[182:185], v[214:217], v[68:71]
	s_barrier
	v_lshl_add_u64 v[166:167], s[78:79], 0, v[132:133]
	s_add_i32 s78, s64, s34
	s_mov_b32 m0, s78
	ds_read_b128 v[186:189], v145 offset:16384
	ds_read_b128 v[190:193], v145 offset:18432
	ds_read_b128 v[194:197], v146 offset:16384
	ds_read_b128 v[198:201], v146 offset:18432
	ds_read_b128 v[202:205], v145 offset:20480
	ds_read_b128 v[206:209], v145 offset:22528
	ds_read_b128 v[210:213], v146 offset:20480
	ds_read_b128 v[214:217], v146 offset:22528
	global_load_lds_dwordx4 v[166:167], off
	v_lshl_add_u64 v[218:219], v[166:167], 0, s[10:11]
	s_add_i32 m0, s78, 0x2000
	s_add_i32 s78, s66, s34
	global_load_lds_dwordx4 v[218:219], off
	v_lshl_add_u64 v[218:219], v[166:167], 0, s[14:15]
	s_mov_b32 m0, s78
	s_nop 0
	global_load_lds_dwordx4 v[218:219], off
	v_lshl_add_u64 v[218:219], v[166:167], 0, s[16:17]
	s_add_i32 m0, s78, 0x2000
	s_nop 0
	global_load_lds_dwordx4 v[218:219], off
	s_waitcnt vmcnt(4)
	s_waitcnt lgkmcnt(0)
	s_barrier
	v_mfma_f32_16x16x32_bf16 v[64:67], v[148:151], v[186:189], v[64:67]
	v_mfma_f32_16x16x32_bf16 v[64:67], v[152:155], v[194:197], v[64:67]
	v_mfma_f32_16x16x32_bf16 v[60:63], v[158:161], v[186:189], v[60:63]
	v_mfma_f32_16x16x32_bf16 v[60:63], v[162:165], v[194:197], v[60:63]
	v_mfma_f32_16x16x32_bf16 v[48:51], v[148:151], v[190:193], v[48:51]
	v_mfma_f32_16x16x32_bf16 v[48:51], v[152:155], v[198:201], v[48:51]
	v_mfma_f32_16x16x32_bf16 v[44:47], v[158:161], v[190:193], v[44:47]
	v_mfma_f32_16x16x32_bf16 v[44:47], v[162:165], v[198:201], v[44:47]
	v_mfma_f32_16x16x32_bf16 v[32:35], v[148:151], v[202:205], v[32:35]
	v_mfma_f32_16x16x32_bf16 v[32:35], v[152:155], v[210:213], v[32:35]
	v_mfma_f32_16x16x32_bf16 v[28:31], v[158:161], v[202:205], v[28:31]
	v_mfma_f32_16x16x32_bf16 v[28:31], v[162:165], v[210:213], v[28:31]
	v_mfma_f32_16x16x32_bf16 v[16:19], v[148:151], v[206:209], v[16:19]
	v_mfma_f32_16x16x32_bf16 v[16:19], v[152:155], v[214:217], v[16:19]
	v_mfma_f32_16x16x32_bf16 v[12:15], v[158:161], v[206:209], v[12:15]
	v_mfma_f32_16x16x32_bf16 v[12:15], v[162:165], v[214:217], v[12:15]
	v_mfma_f32_16x16x32_bf16 v[56:59], v[170:173], v[186:189], v[56:59]
	v_mfma_f32_16x16x32_bf16 v[56:59], v[174:177], v[194:197], v[56:59]
	v_mfma_f32_16x16x32_bf16 v[52:55], v[178:181], v[186:189], v[52:55]
	v_mfma_f32_16x16x32_bf16 v[52:55], v[182:185], v[194:197], v[52:55]
	v_mfma_f32_16x16x32_bf16 v[40:43], v[170:173], v[190:193], v[40:43]
	v_mfma_f32_16x16x32_bf16 v[40:43], v[174:177], v[198:201], v[40:43]
	v_mfma_f32_16x16x32_bf16 v[36:39], v[178:181], v[190:193], v[36:39]
	v_mfma_f32_16x16x32_bf16 v[36:39], v[182:185], v[198:201], v[36:39]
	v_mfma_f32_16x16x32_bf16 v[24:27], v[170:173], v[202:205], v[24:27]
	v_mfma_f32_16x16x32_bf16 v[24:27], v[174:177], v[210:213], v[24:27]
	v_mfma_f32_16x16x32_bf16 v[20:23], v[178:181], v[202:205], v[20:23]
	v_mfma_f32_16x16x32_bf16 v[20:23], v[182:185], v[210:213], v[20:23]
	v_mfma_f32_16x16x32_bf16 v[8:11], v[170:173], v[206:209], v[8:11]
	v_mfma_f32_16x16x32_bf16 v[8:11], v[174:177], v[214:217], v[8:11]
	v_mfma_f32_16x16x32_bf16 v[4:7], v[178:181], v[206:209], v[4:7]
	v_mfma_f32_16x16x32_bf16 v[4:7], v[182:185], v[214:217], v[4:7]
	s_barrier
	v_add_u32_e32 v147, s70, v143
	v_add_u32_e32 v152, s70, v144
	ds_read_b128 v[148:151], v147
	ds_read_b128 v[152:155], v152
	v_add_u32_e32 v147, s68, v143
	v_add_u32_e32 v162, s68, v144
	ds_read_b128 v[158:161], v147
	ds_read_b128 v[162:165], v162
	v_add_u32_e32 v147, s71, v143
	v_add_u32_e32 v169, s71, v144
	ds_read_b128 v[170:173], v147
	ds_read_b128 v[174:177], v169
	v_add_u32_e32 v147, s69, v143
	v_add_u32_e32 v169, s69, v144
	ds_read_b128 v[178:181], v147
	ds_read_b128 v[182:185], v169
	s_mov_b32 m0, s35
	v_lshl_add_u64 v[218:219], s[58:59], 0, v[0:1]
	ds_read_b128 v[186:189], v145 offset:32768
	ds_read_b128 v[190:193], v145 offset:34816
	ds_read_b128 v[194:197], v146 offset:32768
	ds_read_b128 v[198:201], v146 offset:34816
	ds_read_b128 v[202:205], v145 offset:36864
	ds_read_b128 v[206:209], v145 offset:38912
	ds_read_b128 v[210:213], v146 offset:36864
	ds_read_b128 v[214:217], v146 offset:38912
	global_load_lds_dwordx4 v[218:219], off
	v_lshl_add_u64 v[220:221], v[218:219], 0, s[20:21]
	s_mov_b32 m0, s39
	s_nop 0
	global_load_lds_dwordx4 v[220:221], off
	v_lshl_add_u64 v[220:221], v[218:219], 0, s[10:11]
	s_mov_b32 m0, s60
	v_lshl_add_u64 v[218:219], v[218:219], 0, s[22:23]
	global_load_lds_dwordx4 v[220:221], off
	s_mov_b32 m0, s61
	s_nop 0
	global_load_lds_dwordx4 v[218:219], off
	s_waitcnt vmcnt(8)
	s_waitcnt lgkmcnt(0)
	s_barrier
	v_mfma_f32_16x16x32_bf16 v[128:131], v[148:151], v[186:189], v[128:131]
	v_mfma_f32_16x16x32_bf16 v[128:131], v[152:155], v[194:197], v[128:131]
	v_mfma_f32_16x16x32_bf16 v[124:127], v[158:161], v[186:189], v[124:127]
	v_mfma_f32_16x16x32_bf16 v[124:127], v[162:165], v[194:197], v[124:127]
	v_mfma_f32_16x16x32_bf16 v[112:115], v[148:151], v[190:193], v[112:115]
	v_mfma_f32_16x16x32_bf16 v[112:115], v[152:155], v[198:201], v[112:115]
	v_mfma_f32_16x16x32_bf16 v[108:111], v[158:161], v[190:193], v[108:111]
	v_mfma_f32_16x16x32_bf16 v[108:111], v[162:165], v[198:201], v[108:111]
	v_mfma_f32_16x16x32_bf16 v[96:99], v[148:151], v[202:205], v[96:99]
	v_mfma_f32_16x16x32_bf16 v[96:99], v[152:155], v[210:213], v[96:99]
	v_mfma_f32_16x16x32_bf16 v[92:95], v[158:161], v[202:205], v[92:95]
	v_mfma_f32_16x16x32_bf16 v[92:95], v[162:165], v[210:213], v[92:95]
	v_mfma_f32_16x16x32_bf16 v[80:83], v[148:151], v[206:209], v[80:83]
	v_mfma_f32_16x16x32_bf16 v[80:83], v[152:155], v[214:217], v[80:83]
	v_mfma_f32_16x16x32_bf16 v[76:79], v[158:161], v[206:209], v[76:79]
	v_mfma_f32_16x16x32_bf16 v[76:79], v[162:165], v[214:217], v[76:79]
	v_mfma_f32_16x16x32_bf16 v[120:123], v[170:173], v[186:189], v[120:123]
	v_mfma_f32_16x16x32_bf16 v[120:123], v[174:177], v[194:197], v[120:123]
	v_mfma_f32_16x16x32_bf16 v[116:119], v[178:181], v[186:189], v[116:119]
	v_mfma_f32_16x16x32_bf16 v[116:119], v[182:185], v[194:197], v[116:119]
	v_mfma_f32_16x16x32_bf16 v[104:107], v[170:173], v[190:193], v[104:107]
	v_mfma_f32_16x16x32_bf16 v[104:107], v[174:177], v[198:201], v[104:107]
	v_mfma_f32_16x16x32_bf16 v[100:103], v[178:181], v[190:193], v[100:103]
	v_mfma_f32_16x16x32_bf16 v[100:103], v[182:185], v[198:201], v[100:103]
	v_mfma_f32_16x16x32_bf16 v[88:91], v[170:173], v[202:205], v[88:91]
	v_mfma_f32_16x16x32_bf16 v[88:91], v[174:177], v[210:213], v[88:91]
	v_mfma_f32_16x16x32_bf16 v[84:87], v[178:181], v[202:205], v[84:87]
	v_mfma_f32_16x16x32_bf16 v[84:87], v[182:185], v[210:213], v[84:87]
	v_mfma_f32_16x16x32_bf16 v[72:75], v[170:173], v[206:209], v[72:75]
	v_mfma_f32_16x16x32_bf16 v[72:75], v[174:177], v[214:217], v[72:75]
	v_mfma_f32_16x16x32_bf16 v[68:71], v[178:181], v[206:209], v[68:71]
	v_mfma_f32_16x16x32_bf16 v[68:71], v[182:185], v[214:217], v[68:71]
	s_barrier
	s_add_i32 s58, s70, s34
	v_lshl_add_u64 v[218:219], v[166:167], 0, s[24:25]
	s_mov_b32 m0, s58
	ds_read_b128 v[186:189], v145 offset:49152
	ds_read_b128 v[190:193], v145 offset:51200
	ds_read_b128 v[194:197], v146 offset:49152
	ds_read_b128 v[198:201], v146 offset:51200
	ds_read_b128 v[202:205], v145 offset:53248
	ds_read_b128 v[206:209], v145 offset:55296
	ds_read_b128 v[210:213], v146 offset:53248
	ds_read_b128 v[214:217], v146 offset:55296
	global_load_lds_dwordx4 v[218:219], off
	v_lshl_add_u64 v[218:219], v[166:167], 0, s[28:29]
	s_add_i32 m0, s58, 0x2000
	s_add_i32 s58, s71, s34
	global_load_lds_dwordx4 v[218:219], off
	v_lshl_add_u64 v[218:219], v[166:167], 0, s[36:37]
	s_mov_b32 m0, s58
	v_lshl_add_u64 v[166:167], v[166:167], 0, s[40:41]
	global_load_lds_dwordx4 v[218:219], off
	s_add_i32 m0, s58, 0x2000
	s_nop 0
	global_load_lds_dwordx4 v[166:167], off
	s_waitcnt vmcnt(4)
	s_waitcnt lgkmcnt(0)
	s_barrier
	v_mfma_f32_16x16x32_bf16 v[64:67], v[148:151], v[186:189], v[64:67]
	v_mfma_f32_16x16x32_bf16 v[64:67], v[152:155], v[194:197], v[64:67]
	v_mfma_f32_16x16x32_bf16 v[60:63], v[158:161], v[186:189], v[60:63]
	v_mfma_f32_16x16x32_bf16 v[60:63], v[162:165], v[194:197], v[60:63]
	v_mfma_f32_16x16x32_bf16 v[48:51], v[148:151], v[190:193], v[48:51]
	v_mfma_f32_16x16x32_bf16 v[48:51], v[152:155], v[198:201], v[48:51]
	v_mfma_f32_16x16x32_bf16 v[44:47], v[158:161], v[190:193], v[44:47]
	v_mfma_f32_16x16x32_bf16 v[44:47], v[162:165], v[198:201], v[44:47]
	v_mfma_f32_16x16x32_bf16 v[32:35], v[148:151], v[202:205], v[32:35]
	v_mfma_f32_16x16x32_bf16 v[32:35], v[152:155], v[210:213], v[32:35]
	v_mfma_f32_16x16x32_bf16 v[28:31], v[158:161], v[202:205], v[28:31]
	v_mfma_f32_16x16x32_bf16 v[28:31], v[162:165], v[210:213], v[28:31]
	v_mfma_f32_16x16x32_bf16 v[16:19], v[148:151], v[206:209], v[16:19]
	v_mfma_f32_16x16x32_bf16 v[16:19], v[152:155], v[214:217], v[16:19]
	v_mfma_f32_16x16x32_bf16 v[12:15], v[158:161], v[206:209], v[12:15]
	v_mfma_f32_16x16x32_bf16 v[12:15], v[162:165], v[214:217], v[12:15]
	v_mfma_f32_16x16x32_bf16 v[56:59], v[170:173], v[186:189], v[56:59]
	v_mfma_f32_16x16x32_bf16 v[56:59], v[174:177], v[194:197], v[56:59]
	v_mfma_f32_16x16x32_bf16 v[52:55], v[178:181], v[186:189], v[52:55]
	v_mfma_f32_16x16x32_bf16 v[52:55], v[182:185], v[194:197], v[52:55]
	v_mfma_f32_16x16x32_bf16 v[40:43], v[170:173], v[190:193], v[40:43]
	v_mfma_f32_16x16x32_bf16 v[40:43], v[174:177], v[198:201], v[40:43]
	v_mfma_f32_16x16x32_bf16 v[36:39], v[178:181], v[190:193], v[36:39]
	v_mfma_f32_16x16x32_bf16 v[36:39], v[182:185], v[198:201], v[36:39]
	v_mfma_f32_16x16x32_bf16 v[24:27], v[170:173], v[202:205], v[24:27]
	v_mfma_f32_16x16x32_bf16 v[24:27], v[174:177], v[210:213], v[24:27]
	v_mfma_f32_16x16x32_bf16 v[20:23], v[178:181], v[202:205], v[20:23]
	v_mfma_f32_16x16x32_bf16 v[20:23], v[182:185], v[210:213], v[20:23]
	v_mfma_f32_16x16x32_bf16 v[8:11], v[170:173], v[206:209], v[8:11]
	v_mfma_f32_16x16x32_bf16 v[8:11], v[174:177], v[214:217], v[8:11]
	v_mfma_f32_16x16x32_bf16 v[4:7], v[178:181], v[206:209], v[4:7]
	v_mfma_f32_16x16x32_bf16 v[4:7], v[182:185], v[214:217], v[4:7]
	s_barrier
	s_add_i32 s77, s77, 2
	s_add_u32 s56, s56, 0x100
	s_addc_u32 s57, s57, 0
	s_cmp_gt_u32 s77, 61
	s_cbranch_scc0 .LBB0_1371
	s_add_u32 s56, s53, 0xffffff00
	s_addc_u32 s57, s72, -1
	s_andn2_b64 vcc, exec, s[6:7]
	s_cbranch_vccnz .LBB0_1362
	v_mov_b32_e32 v4, 0
	s_mov_b32 s0, s48
	s_mov_b32 s8, s50
	s_mov_b64 s[18:19], s[54:55]
	s_mov_b32 s63, s52
	v_mov_b32_e32 v5, v4
	v_mov_b32_e32 v6, v4
	v_mov_b32_e32 v7, v4
	v_mov_b32_e32 v8, v4
	v_mov_b32_e32 v9, v4
	v_mov_b32_e32 v10, v4
	v_mov_b32_e32 v11, v4
	v_mov_b32_e32 v20, v4
	v_mov_b32_e32 v21, v4
	v_mov_b32_e32 v22, v4
	v_mov_b32_e32 v23, v4
	v_mov_b32_e32 v24, v4
	v_mov_b32_e32 v25, v4
	v_mov_b32_e32 v26, v4
	v_mov_b32_e32 v27, v4
	v_mov_b32_e32 v36, v4
	v_mov_b32_e32 v37, v4
	v_mov_b32_e32 v38, v4
	v_mov_b32_e32 v39, v4
	v_mov_b32_e32 v40, v4
	v_mov_b32_e32 v41, v4
	v_mov_b32_e32 v42, v4
	v_mov_b32_e32 v43, v4
	v_mov_b32_e32 v52, v4
	v_mov_b32_e32 v53, v4
	v_mov_b32_e32 v54, v4
	v_mov_b32_e32 v55, v4
	v_mov_b32_e32 v56, v4
	v_mov_b32_e32 v57, v4
	v_mov_b32_e32 v58, v4
	v_mov_b32_e32 v59, v4
	v_mov_b32_e32 v12, v4
	v_mov_b32_e32 v13, v4
	v_mov_b32_e32 v14, v4
	v_mov_b32_e32 v15, v4
	v_mov_b32_e32 v16, v4
	v_mov_b32_e32 v17, v4
	v_mov_b32_e32 v18, v4
	v_mov_b32_e32 v19, v4
	v_mov_b32_e32 v28, v4
	v_mov_b32_e32 v29, v4
	v_mov_b32_e32 v30, v4
	v_mov_b32_e32 v31, v4
	v_mov_b32_e32 v32, v4
	v_mov_b32_e32 v33, v4
	v_mov_b32_e32 v34, v4
	v_mov_b32_e32 v35, v4
	v_mov_b32_e32 v44, v4
	v_mov_b32_e32 v45, v4
	v_mov_b32_e32 v46, v4
	v_mov_b32_e32 v47, v4
	v_mov_b32_e32 v48, v4
	v_mov_b32_e32 v49, v4
	v_mov_b32_e32 v50, v4
	v_mov_b32_e32 v51, v4
	v_mov_b32_e32 v60, v4
	v_mov_b32_e32 v61, v4
	v_mov_b32_e32 v62, v4
	v_mov_b32_e32 v63, v4
	v_mov_b32_e32 v64, v4
	v_mov_b32_e32 v65, v4
	v_mov_b32_e32 v66, v4
	v_mov_b32_e32 v67, v4
	v_mov_b32_e32 v68, v4
	v_mov_b32_e32 v69, v4
	v_mov_b32_e32 v70, v4
	v_mov_b32_e32 v71, v4
	v_mov_b32_e32 v72, v4
	v_mov_b32_e32 v73, v4
	v_mov_b32_e32 v74, v4
	v_mov_b32_e32 v75, v4
	v_mov_b32_e32 v84, v4
	v_mov_b32_e32 v85, v4
	v_mov_b32_e32 v86, v4
	v_mov_b32_e32 v87, v4
	v_mov_b32_e32 v88, v4
	v_mov_b32_e32 v89, v4
	v_mov_b32_e32 v90, v4
	v_mov_b32_e32 v91, v4
	v_mov_b32_e32 v100, v4
	v_mov_b32_e32 v101, v4
	v_mov_b32_e32 v102, v4
	v_mov_b32_e32 v103, v4
	v_mov_b32_e32 v104, v4
	v_mov_b32_e32 v105, v4
	v_mov_b32_e32 v106, v4
	v_mov_b32_e32 v107, v4
	v_mov_b32_e32 v116, v4
	v_mov_b32_e32 v117, v4
	v_mov_b32_e32 v118, v4
	v_mov_b32_e32 v119, v4
	v_mov_b32_e32 v120, v4
	v_mov_b32_e32 v121, v4
	v_mov_b32_e32 v122, v4
	v_mov_b32_e32 v123, v4
	v_mov_b32_e32 v76, v4
	v_mov_b32_e32 v77, v4
	v_mov_b32_e32 v78, v4
	v_mov_b32_e32 v79, v4
	v_mov_b32_e32 v80, v4
	v_mov_b32_e32 v81, v4
	v_mov_b32_e32 v82, v4
	v_mov_b32_e32 v83, v4
	v_mov_b32_e32 v92, v4
	v_mov_b32_e32 v93, v4
	v_mov_b32_e32 v94, v4
	v_mov_b32_e32 v95, v4
	v_mov_b32_e32 v96, v4
	v_mov_b32_e32 v97, v4
	v_mov_b32_e32 v98, v4
	v_mov_b32_e32 v99, v4
	v_mov_b32_e32 v108, v4
	v_mov_b32_e32 v109, v4
	v_mov_b32_e32 v110, v4
	v_mov_b32_e32 v111, v4
	v_mov_b32_e32 v112, v4
	v_mov_b32_e32 v113, v4
	v_mov_b32_e32 v114, v4
	v_mov_b32_e32 v115, v4
	v_mov_b32_e32 v124, v4
	v_mov_b32_e32 v125, v4
	v_mov_b32_e32 v126, v4
	v_mov_b32_e32 v127, v4
	v_mov_b32_e32 v128, v4
	v_mov_b32_e32 v129, v4
	v_mov_b32_e32 v130, v4
	v_mov_b32_e32 v131, v4
	s_andn2_b64 vcc, exec, s[4:5]
	s_cbranch_vccnz .LBB0_1363
